# v7
# speedup vs baseline: 1.0613x; 1.0315x over previous
; __device__ __forceinline__ float rstd8(const float* q) {
;   const float4 a = *(const float4*)q, b = *(const float4*)(q + 4);
;   return rsqrtf((((a.x + a.y) + (a.z + a.w)) + ((b.x + b.y) + (b.z + b.w))) * (1.f / DM) + EPS);
; }
;     ...
;       const int cls = brow >> 10;
;       const int nb = brow & 1023;
;       const float* gp = (cls == 0 ? pq->sb_q_gain : pq->sb_k_gain) + jq * 64;
;       const float sc = (cls == 0) ? (0.125f * 1.4426950408889634f) : 1.f;
;       u16* Qn = pq->xbc; u16* Kn = pq->xbc + (long)TT * DM;
;       for (int bj = 0; bj < 2; ++bj) for (int nn = 0; nn < 2; ++nn) {
;         const long tok = bcol + bj * HALF + wc * 32 + nn * 16 + efr;
;         const float rs = rstd8(ssq_in + tok * 8);
;         const bool prompt = tok < TP;
;         for (int ai = 0; ai < 2; ++ai) {
;           float hr = 1.f;
;           if (cls < 2) {
;             float ss = 0.f;
;             for (int m = 0; m < 4; ++m) for (int jj = 0; jj < 4; ++jj) { const float t = acc[ai][bj][m][nn][jj] * rs; ss += t * t; }
;             ss += __shfl_xor(ss, 16); ss += __shfl_xor(ss, 32);
;             hr = rsqrtf(ss * (1.f / 64.f) + EPS) * sc;
;           }
;           for (int m = 0; m < 4; ++m) {
;             const int n = nb + ai * HALF + wr * 64 + m * 16 + efq * 4;
;             float4 g4 = make_float4(1.f, 1.f, 1.f, 1.f);
;             if (cls < 2) g4 = *(const float4*)(gp + m * 16 + efq * 4);
;             const float o0 = acc[ai][bj][m][nn][0] * rs * hr * g4.x, o1 = acc[ai][bj][m][nn][1] * rs * hr * g4.y;
;             const float o2 = acc[ai][bj][m][nn][2] * rs * hr * g4.z, o3 = acc[ai][bj][m][nn][3] * rs * hr * g4.w;
;             uint2 pk; pk.x = pack2(o0, o1); pk.y = pack2(o2, o3);
;             if (cls == 0) { *(uint2*)(Qn + tok * DM + n) = pk; }
;             else {
;               float* of = pq->out + (cls == 1 ? (prompt ? O_PK + ((long)jq * TP + tok) * DM : O_SK + ((long)jq * TS + (tok - TP)) * DM)
;                                               : (prompt ? O_PV + ((long)jq * TP + tok) * DM : O_SV + ((long)jq * TS + (tok - TP)) * DM)) + n;
;               *(float4*)of = make_float4(o0, o1, o2, o3);
;               if (prompt) {
;                 if (cls == 1) *(uint2*)(Kn + tok * DM + n) = pk;
;                 else *(uint2*)(outb + tok * ldo + 2048 + n) = pk;
.LBB0_657:
	s_or_b64 exec, exec, s[12:13]
	s_cmp_ge_u32 s10, 0x10000
	s_cbranch_scc1 .Lmy_qkv_slow
	v_and_b32_e32 v146, 15, v0
	v_add3_u32 v144, s10, v201, v146
	v_ashrrev_i32_e32 v145, 31, v144
	v_lshlrev_b64 v[134:135], 5, v[144:145]
	v_lshl_add_u64 v[134:135], s[20:21], 0, v[134:135]
	v_add_u32_e32 v136, 0x80, v144
	v_ashrrev_i32_e32 v137, 31, v136
	v_lshlrev_b64 v[136:137], 5, v[136:137]
	v_lshl_add_u64 v[136:137], s[20:21], 0, v[136:137]
	global_load_dwordx4 v[150:153], v[134:135], off
	global_load_dwordx4 v[154:157], v[134:135], off offset:16
	global_load_dwordx4 v[158:161], v[134:135], off offset:512
	global_load_dwordx4 v[162:165], v[134:135], off offset:528
	global_load_dwordx4 v[166:169], v[136:137], off
	global_load_dwordx4 v[170:173], v[136:137], off offset:16
	global_load_dwordx4 v[174:177], v[136:137], off offset:512
	global_load_dwordx4 v[178:181], v[136:137], off offset:528
	s_ashr_i32 s5, s4, 10
	s_and_b32 s4, s4, 0x3ff
	s_cmp_gt_i32 s5, 1
	s_cbranch_scc1 .Lmy_qkv_nogain
	v_readlane_b32 s52, v254, 55
	v_readlane_b32 s53, v254, 56
	v_readlane_b32 s54, v254, 57
	v_readlane_b32 s55, v254, 58
	v_readlane_b32 s56, v255, 41
	v_readlane_b32 s57, v255, 42
	s_cmp_eq_u32 s5, 0
	s_cselect_b32 s52, s52, s54
	s_cselect_b32 s53, s53, s55
	s_add_u32 s52, s52, s56
	s_addc_u32 s53, s53, s57
	v_lshrrev_b32_e32 v138, 4, v0
	v_lshlrev_b32_e32 v138, 4, v138
	v_mov_b32_e32 v139, 0
	v_lshl_add_u64 v[138:139], s[52:53], 0, v[138:139]
	global_load_dwordx4 v[182:185], v[138:139], off
	global_load_dwordx4 v[186:189], v[138:139], off offset:64
	global_load_dwordx4 v[190:193], v[138:139], off offset:128
	global_load_dwordx4 v[194:197], v[138:139], off offset:192
.Lmy_qkv_nogain:
	v_lshrrev_b32_e32 v138, 4, v0
	v_and_b32_e32 v139, 1, v138
	v_lshlrev_b32_e32 v139, 5, v139
	v_lshrrev_b32_e32 v146, 1, v138
	v_lshl_add_u32 v139, v146, 4, v139
	v_add_u32_e32 v146, s4, v200
	v_lshl_add_u32 v147, v138, 2, v146
	v_lshlrev_b32_e32 v147, 2, v147
	v_lshl_add_u32 v138, v146, 1, v139
	v_mov_b32_e32 v139, 0
	v_mov_b32_e32 v149, 0
	v_xor_b32_e32 v135, 16, v0
	v_lshlrev_b32_e32 v135, 2, v135
	v_xor_b32_e32 v136, 32, v0
	v_lshlrev_b32_e32 v136, 2, v136
	v_mov_b32_e32 v137, 0x358637bd
	s_waitcnt vmcnt(0)
	v_add_f32_e32 v150, v150, v151
	v_add_f32_e32 v152, v152, v153
	v_add_f32_e32 v154, v154, v155
	v_add_f32_e32 v156, v156, v157
	v_add_f32_e32 v150, v150, v152
	v_add_f32_e32 v154, v154, v156
	v_add_f32_e32 v150, v150, v154
	v_fmamk_f32 v150, v150, 0x3a800000, v137
	v_add_f32_e32 v158, v158, v159
	v_add_f32_e32 v160, v160, v161
	v_add_f32_e32 v162, v162, v163
	v_add_f32_e32 v164, v164, v165
	v_add_f32_e32 v158, v158, v160
	v_add_f32_e32 v162, v162, v164
	v_add_f32_e32 v158, v158, v162
	v_fmamk_f32 v158, v158, 0x3a800000, v137
	v_add_f32_e32 v166, v166, v167
	v_add_f32_e32 v168, v168, v169
	v_add_f32_e32 v170, v170, v171
	v_add_f32_e32 v172, v172, v173
	v_add_f32_e32 v166, v166, v168
	v_add_f32_e32 v170, v170, v172
	v_add_f32_e32 v166, v166, v170
	v_fmamk_f32 v166, v166, 0x3a800000, v137
	v_add_f32_e32 v174, v174, v175
	v_add_f32_e32 v176, v176, v177
	v_add_f32_e32 v178, v178, v179
	v_add_f32_e32 v180, v180, v181
	v_add_f32_e32 v174, v174, v176
	v_add_f32_e32 v178, v178, v180
	v_add_f32_e32 v174, v174, v178
	v_fmamk_f32 v174, v174, 0x3a800000, v137
	v_rsq_f32_e32 v150, v150
	v_rsq_f32_e32 v152, v158
	v_rsq_f32_e32 v154, v166
	v_rsq_f32_e32 v156, v174
	s_cmp_eq_u32 s5, 2
	s_cbranch_scc1 .Lmy_qkv_vbase
	v_readlane_b32 s52, v255, 5
	v_readlane_b32 s53, v255, 6
	s_cmp_eq_u32 s5, 0
	s_cselect_b32 s52, s52, s38
	s_cselect_b32 s53, s53, s39
	v_lshlrev_b64 v[166:167], 11, v[144:145]
	v_lshl_add_u64 v[166:167], s[52:53], 0, v[166:167]
	v_lshl_add_u64 v[166:167], v[166:167], 0, v[138:139]
	v_mov_b32_e32 v148, 0x8000
	v_lshl_add_u64 v[168:169], v[166:167], 0, v[148:149]
	v_mov_b32_e32 v148, 0x40000
	v_lshl_add_u64 v[170:171], v[166:167], 0, v[148:149]
	v_mov_b32_e32 v148, 0x48000
	v_lshl_add_u64 v[172:173], v[166:167], 0, v[148:149]
	s_branch .Lmy_qkv_f32base
.Lmy_qkv_vbase:
	v_mov_b64_e32 v[166:167], s[80:81]
	v_mad_i64_i32 v[166:167], vcc, v144, s96, v[166:167]
	v_mov_b32_e32 v148, 0x1000
	v_lshl_add_u64 v[166:167], v[166:167], 0, v[148:149]
	v_lshl_add_u64 v[166:167], v[166:167], 0, v[138:139]
	v_mov_b32_e32 v148, 0x18000
	v_lshl_add_u64 v[168:169], v[166:167], 0, v[148:149]
	v_mov_b32_e32 v148, 0xc0000
	v_lshl_add_u64 v[170:171], v[166:167], 0, v[148:149]
	v_mov_b32_e32 v148, 0xd8000
	v_lshl_add_u64 v[172:173], v[166:167], 0, v[148:149]
.Lmy_qkv_f32base:
	s_cmp_eq_u32 s5, 0
	s_cbranch_scc1 .Lmy_qkv_bases_done
	v_readlane_b32 s54, v255, 38
	v_readlane_b32 s55, v255, 39
	v_readlane_b32 s56, v255, 1
	v_readlane_b32 s57, v255, 2
	s_cmp_eq_u32 s5, 1
	s_cselect_b32 s54, s30, s54
	s_cselect_b32 s55, s31, s55
	v_lshlrev_b64 v[158:159], 10, v[144:145]
	v_lshl_add_u64 v[158:159], v[158:159], 0, s[54:55]
	v_lshl_add_u64 v[158:159], v[158:159], 2, s[56:57]
	v_mov_b32_e32 v146, v147
	v_mov_b32_e32 v147, 0
	v_lshl_add_u64 v[158:159], v[158:159], 0, v[146:147]
	v_mov_b32_e32 v148, 0x10000
	v_lshl_add_u64 v[160:161], v[158:159], 0, v[148:149]
	v_mov_b32_e32 v148, 0x80000
	v_lshl_add_u64 v[162:163], v[158:159], 0, v[148:149]
	v_mov_b32_e32 v148, 0x90000
	v_lshl_add_u64 v[164:165], v[158:159], 0, v[148:149]
; __device__ __forceinline__ uint32_t pack2(float a, float b) { return (uint32_t)f2bf(a) | ((uint32_t)f2bf(b) << 16); }
;     ...
;           for (int m = 0; m < 4; ++m) {
;             const int n = nb + ai * HALF + wr * 64 + m * 16 + efq * 4;
;             float4 g4 = make_float4(1.f, 1.f, 1.f, 1.f);
;             if (cls < 2) g4 = *(const float4*)(gp + m * 16 + efq * 4);
;             const float o0 = acc[ai][bj][m][nn][0] * rs * hr * g4.x, o1 = acc[ai][bj][m][nn][1] * rs * hr * g4.y;
;             const float o2 = acc[ai][bj][m][nn][2] * rs * hr * g4.z, o3 = acc[ai][bj][m][nn][3] * rs * hr * g4.w;
;             uint2 pk; pk.x = pack2(o0, o1); pk.y = pack2(o2, o3);
;             if (cls == 0) { *(uint2*)(Qn + tok * DM + n) = pk; }
;             else {
;               float* of = pq->out + (cls == 1 ? (prompt ? O_PK + ((long)jq * TP + tok) * DM : O_SK + ((long)jq * TS + (tok - TP)) * DM)
;                                               : (prompt ? O_PV + ((long)jq * TP + tok) * DM : O_SV + ((long)jq * TS + (tok - TP)) * DM)) + n;
;               *(float4*)of = make_float4(o0, o1, o2, o3);
;               if (prompt) {
;                 if (cls == 1) *(uint2*)(Kn + tok * DM + n) = pk;
;                 else *(uint2*)(outb + tok * ldo + 2048 + n) = pk;
.Lmy_qkv_bases_done:
	s_cmp_eq_u32 s5, 0
	s_cbranch_scc1 .Lmy_qkv_q
	s_cmp_eq_u32 s5, 1
	s_cbranch_scc1 .Lmy_qkv_k
	v_pk_mul_f32 v[126:127], v[126:127], v[150:151] op_sel_hi:[1,0]
	v_pk_mul_f32 v[128:129], v[128:129], v[150:151] op_sel_hi:[1,0]
	v_pk_mul_f32 v[122:123], v[122:123], v[150:151] op_sel_hi:[1,0]
	v_pk_mul_f32 v[124:125], v[124:125], v[150:151] op_sel_hi:[1,0]
	v_pk_mul_f32 v[118:119], v[118:119], v[150:151] op_sel_hi:[1,0]
	v_pk_mul_f32 v[120:121], v[120:121], v[150:151] op_sel_hi:[1,0]
	v_pk_mul_f32 v[114:115], v[114:115], v[150:151] op_sel_hi:[1,0]
	v_pk_mul_f32 v[116:117], v[116:117], v[150:151] op_sel_hi:[1,0]
	global_store_dwordx4 v[158:159], v[126:129], off
	global_store_dwordx4 v[158:159], v[122:125], off offset:64
	global_store_dwordx4 v[158:159], v[118:121], off offset:128
	global_store_dwordx4 v[158:159], v[114:117], off offset:192
	v_cvt_pk_bf16_f32 v130, v126, v127
	v_cvt_pk_bf16_f32 v131, v128, v129
	v_cvt_pk_bf16_f32 v132, v122, v123
	v_cvt_pk_bf16_f32 v133, v124, v125
	s_nop 1
	v_permlane16_swap_b32_e32 v130, v132
	v_permlane16_swap_b32_e32 v131, v133
	global_store_dwordx4 v[166:167], v[130:133], off
	v_cvt_pk_bf16_f32 v140, v118, v119
	v_cvt_pk_bf16_f32 v141, v120, v121
	v_cvt_pk_bf16_f32 v142, v114, v115
	v_cvt_pk_bf16_f32 v143, v116, v117
	s_nop 1
	v_permlane16_swap_b32_e32 v140, v142
	v_permlane16_swap_b32_e32 v141, v143
	global_store_dwordx4 v[166:167], v[140:143], off offset:64
	v_pk_mul_f32 v[110:111], v[110:111], v[150:151] op_sel_hi:[1,0]
	v_pk_mul_f32 v[112:113], v[112:113], v[150:151] op_sel_hi:[1,0]
	v_pk_mul_f32 v[106:107], v[106:107], v[150:151] op_sel_hi:[1,0]
	v_pk_mul_f32 v[108:109], v[108:109], v[150:151] op_sel_hi:[1,0]
	v_pk_mul_f32 v[102:103], v[102:103], v[150:151] op_sel_hi:[1,0]
	v_pk_mul_f32 v[104:105], v[104:105], v[150:151] op_sel_hi:[1,0]
	v_pk_mul_f32 v[98:99], v[98:99], v[150:151] op_sel_hi:[1,0]
	v_pk_mul_f32 v[100:101], v[100:101], v[150:151] op_sel_hi:[1,0]
	global_store_dwordx4 v[158:159], v[110:113], off offset:512
	global_store_dwordx4 v[158:159], v[106:109], off offset:576
	global_store_dwordx4 v[158:159], v[102:105], off offset:640
	global_store_dwordx4 v[158:159], v[98:101], off offset:704
	v_cvt_pk_bf16_f32 v130, v110, v111
	v_cvt_pk_bf16_f32 v131, v112, v113
	v_cvt_pk_bf16_f32 v132, v106, v107
	v_cvt_pk_bf16_f32 v133, v108, v109
	s_nop 1
	v_permlane16_swap_b32_e32 v130, v132
	v_permlane16_swap_b32_e32 v131, v133
	global_store_dwordx4 v[166:167], v[130:133], off offset:256
	v_cvt_pk_bf16_f32 v140, v102, v103
	v_cvt_pk_bf16_f32 v141, v104, v105
	v_cvt_pk_bf16_f32 v142, v98, v99
	v_cvt_pk_bf16_f32 v143, v100, v101
	s_nop 1
	v_permlane16_swap_b32_e32 v140, v142
	v_permlane16_swap_b32_e32 v141, v143
	global_store_dwordx4 v[166:167], v[140:143], off offset:320
	v_pk_mul_f32 v[94:95], v[94:95], v[152:153] op_sel_hi:[1,0]
	v_pk_mul_f32 v[96:97], v[96:97], v[152:153] op_sel_hi:[1,0]
	v_pk_mul_f32 v[90:91], v[90:91], v[152:153] op_sel_hi:[1,0]
	v_pk_mul_f32 v[92:93], v[92:93], v[152:153] op_sel_hi:[1,0]
	v_pk_mul_f32 v[86:87], v[86:87], v[152:153] op_sel_hi:[1,0]
	v_pk_mul_f32 v[88:89], v[88:89], v[152:153] op_sel_hi:[1,0]
	v_pk_mul_f32 v[82:83], v[82:83], v[152:153] op_sel_hi:[1,0]
	v_pk_mul_f32 v[84:85], v[84:85], v[152:153] op_sel_hi:[1,0]
	global_store_dwordx4 v[160:161], v[94:97], off
	global_store_dwordx4 v[160:161], v[90:93], off offset:64
	global_store_dwordx4 v[160:161], v[86:89], off offset:128
	global_store_dwordx4 v[160:161], v[82:85], off offset:192
	v_cvt_pk_bf16_f32 v130, v94, v95
	v_cvt_pk_bf16_f32 v131, v96, v97
	v_cvt_pk_bf16_f32 v132, v90, v91
	v_cvt_pk_bf16_f32 v133, v92, v93
	s_nop 1
	v_permlane16_swap_b32_e32 v130, v132
	v_permlane16_swap_b32_e32 v131, v133
	global_store_dwordx4 v[168:169], v[130:133], off
	v_cvt_pk_bf16_f32 v140, v86, v87
	v_cvt_pk_bf16_f32 v141, v88, v89
	v_cvt_pk_bf16_f32 v142, v82, v83
	v_cvt_pk_bf16_f32 v143, v84, v85
	s_nop 1
	v_permlane16_swap_b32_e32 v140, v142
	v_permlane16_swap_b32_e32 v141, v143
	global_store_dwordx4 v[168:169], v[140:143], off offset:64
	v_pk_mul_f32 v[78:79], v[78:79], v[152:153] op_sel_hi:[1,0]
	v_pk_mul_f32 v[80:81], v[80:81], v[152:153] op_sel_hi:[1,0]
	v_pk_mul_f32 v[74:75], v[74:75], v[152:153] op_sel_hi:[1,0]
	v_pk_mul_f32 v[76:77], v[76:77], v[152:153] op_sel_hi:[1,0]
	v_pk_mul_f32 v[70:71], v[70:71], v[152:153] op_sel_hi:[1,0]
	v_pk_mul_f32 v[72:73], v[72:73], v[152:153] op_sel_hi:[1,0]
	v_pk_mul_f32 v[66:67], v[66:67], v[152:153] op_sel_hi:[1,0]
	v_pk_mul_f32 v[68:69], v[68:69], v[152:153] op_sel_hi:[1,0]
	global_store_dwordx4 v[160:161], v[78:81], off offset:512
	global_store_dwordx4 v[160:161], v[74:77], off offset:576
	global_store_dwordx4 v[160:161], v[70:73], off offset:640
	global_store_dwordx4 v[160:161], v[66:69], off offset:704
	v_cvt_pk_bf16_f32 v130, v78, v79
	v_cvt_pk_bf16_f32 v131, v80, v81
	v_cvt_pk_bf16_f32 v132, v74, v75
	v_cvt_pk_bf16_f32 v133, v76, v77
	s_nop 1
	v_permlane16_swap_b32_e32 v130, v132
	v_permlane16_swap_b32_e32 v131, v133
	global_store_dwordx4 v[168:169], v[130:133], off offset:256
	v_cvt_pk_bf16_f32 v140, v70, v71
	v_cvt_pk_bf16_f32 v141, v72, v73
	v_cvt_pk_bf16_f32 v142, v66, v67
	v_cvt_pk_bf16_f32 v143, v68, v69
	s_nop 1
	v_permlane16_swap_b32_e32 v140, v142
	v_permlane16_swap_b32_e32 v141, v143
	global_store_dwordx4 v[168:169], v[140:143], off offset:320
	v_pk_mul_f32 v[62:63], v[62:63], v[154:155] op_sel_hi:[1,0]
	v_pk_mul_f32 v[64:65], v[64:65], v[154:155] op_sel_hi:[1,0]
	v_pk_mul_f32 v[58:59], v[58:59], v[154:155] op_sel_hi:[1,0]
	v_pk_mul_f32 v[60:61], v[60:61], v[154:155] op_sel_hi:[1,0]
	v_pk_mul_f32 v[54:55], v[54:55], v[154:155] op_sel_hi:[1,0]
; __device__ __forceinline__ uint32_t pack2(float a, float b) { return (uint32_t)f2bf(a) | ((uint32_t)f2bf(b) << 16); }
;     ...
;           for (int m = 0; m < 4; ++m) {
;             const int n = nb + ai * HALF + wr * 64 + m * 16 + efq * 4;
;             float4 g4 = make_float4(1.f, 1.f, 1.f, 1.f);
;             if (cls < 2) g4 = *(const float4*)(gp + m * 16 + efq * 4);
;             const float o0 = acc[ai][bj][m][nn][0] * rs * hr * g4.x, o1 = acc[ai][bj][m][nn][1] * rs * hr * g4.y;
;             const float o2 = acc[ai][bj][m][nn][2] * rs * hr * g4.z, o3 = acc[ai][bj][m][nn][3] * rs * hr * g4.w;
;             uint2 pk; pk.x = pack2(o0, o1); pk.y = pack2(o2, o3);
;             if (cls == 0) { *(uint2*)(Qn + tok * DM + n) = pk; }
;             else {
;               float* of = pq->out + (cls == 1 ? (prompt ? O_PK + ((long)jq * TP + tok) * DM : O_SK + ((long)jq * TS + (tok - TP)) * DM)
;                                               : (prompt ? O_PV + ((long)jq * TP + tok) * DM : O_SV + ((long)jq * TS + (tok - TP)) * DM)) + n;
;               *(float4*)of = make_float4(o0, o1, o2, o3);
;               if (prompt) {
;                 if (cls == 1) *(uint2*)(Kn + tok * DM + n) = pk;
;                 else *(uint2*)(outb + tok * ldo + 2048 + n) = pk;
	v_pk_mul_f32 v[56:57], v[56:57], v[154:155] op_sel_hi:[1,0]
	v_pk_mul_f32 v[50:51], v[50:51], v[154:155] op_sel_hi:[1,0]
	v_pk_mul_f32 v[52:53], v[52:53], v[154:155] op_sel_hi:[1,0]
	global_store_dwordx4 v[162:163], v[62:65], off
	global_store_dwordx4 v[162:163], v[58:61], off offset:64
	global_store_dwordx4 v[162:163], v[54:57], off offset:128
	global_store_dwordx4 v[162:163], v[50:53], off offset:192
	v_cvt_pk_bf16_f32 v130, v62, v63
	v_cvt_pk_bf16_f32 v131, v64, v65
	v_cvt_pk_bf16_f32 v132, v58, v59
	v_cvt_pk_bf16_f32 v133, v60, v61
	s_nop 1
	v_permlane16_swap_b32_e32 v130, v132
	v_permlane16_swap_b32_e32 v131, v133
	global_store_dwordx4 v[170:171], v[130:133], off
	v_cvt_pk_bf16_f32 v140, v54, v55
	v_cvt_pk_bf16_f32 v141, v56, v57
	v_cvt_pk_bf16_f32 v142, v50, v51
	v_cvt_pk_bf16_f32 v143, v52, v53
	s_nop 1
	v_permlane16_swap_b32_e32 v140, v142
	v_permlane16_swap_b32_e32 v141, v143
	global_store_dwordx4 v[170:171], v[140:143], off offset:64
	v_pk_mul_f32 v[46:47], v[46:47], v[154:155] op_sel_hi:[1,0]
	v_pk_mul_f32 v[48:49], v[48:49], v[154:155] op_sel_hi:[1,0]
	v_pk_mul_f32 v[42:43], v[42:43], v[154:155] op_sel_hi:[1,0]
	v_pk_mul_f32 v[44:45], v[44:45], v[154:155] op_sel_hi:[1,0]
	v_pk_mul_f32 v[38:39], v[38:39], v[154:155] op_sel_hi:[1,0]
	v_pk_mul_f32 v[40:41], v[40:41], v[154:155] op_sel_hi:[1,0]
	v_pk_mul_f32 v[34:35], v[34:35], v[154:155] op_sel_hi:[1,0]
	v_pk_mul_f32 v[36:37], v[36:37], v[154:155] op_sel_hi:[1,0]
	global_store_dwordx4 v[162:163], v[46:49], off offset:512
	global_store_dwordx4 v[162:163], v[42:45], off offset:576
	global_store_dwordx4 v[162:163], v[38:41], off offset:640
	global_store_dwordx4 v[162:163], v[34:37], off offset:704
	v_cvt_pk_bf16_f32 v130, v46, v47
	v_cvt_pk_bf16_f32 v131, v48, v49
	v_cvt_pk_bf16_f32 v132, v42, v43
	v_cvt_pk_bf16_f32 v133, v44, v45
	s_nop 1
	v_permlane16_swap_b32_e32 v130, v132
	v_permlane16_swap_b32_e32 v131, v133
	global_store_dwordx4 v[170:171], v[130:133], off offset:256
	v_cvt_pk_bf16_f32 v140, v38, v39
	v_cvt_pk_bf16_f32 v141, v40, v41
	v_cvt_pk_bf16_f32 v142, v34, v35
	v_cvt_pk_bf16_f32 v143, v36, v37
	s_nop 1
	v_permlane16_swap_b32_e32 v140, v142
	v_permlane16_swap_b32_e32 v141, v143
	global_store_dwordx4 v[170:171], v[140:143], off offset:320
	v_pk_mul_f32 v[30:31], v[30:31], v[156:157] op_sel_hi:[1,0]
	v_pk_mul_f32 v[32:33], v[32:33], v[156:157] op_sel_hi:[1,0]
	v_pk_mul_f32 v[26:27], v[26:27], v[156:157] op_sel_hi:[1,0]
	v_pk_mul_f32 v[28:29], v[28:29], v[156:157] op_sel_hi:[1,0]
	v_pk_mul_f32 v[22:23], v[22:23], v[156:157] op_sel_hi:[1,0]
	v_pk_mul_f32 v[24:25], v[24:25], v[156:157] op_sel_hi:[1,0]
	v_pk_mul_f32 v[18:19], v[18:19], v[156:157] op_sel_hi:[1,0]
	v_pk_mul_f32 v[20:21], v[20:21], v[156:157] op_sel_hi:[1,0]
	global_store_dwordx4 v[164:165], v[30:33], off
	global_store_dwordx4 v[164:165], v[26:29], off offset:64
	global_store_dwordx4 v[164:165], v[22:25], off offset:128
	global_store_dwordx4 v[164:165], v[18:21], off offset:192
	v_cvt_pk_bf16_f32 v130, v30, v31
	v_cvt_pk_bf16_f32 v131, v32, v33
	v_cvt_pk_bf16_f32 v132, v26, v27
	v_cvt_pk_bf16_f32 v133, v28, v29
	s_nop 1
	v_permlane16_swap_b32_e32 v130, v132
	v_permlane16_swap_b32_e32 v131, v133
	global_store_dwordx4 v[172:173], v[130:133], off
	v_cvt_pk_bf16_f32 v140, v22, v23
	v_cvt_pk_bf16_f32 v141, v24, v25
	v_cvt_pk_bf16_f32 v142, v18, v19
	v_cvt_pk_bf16_f32 v143, v20, v21
	s_nop 1
	v_permlane16_swap_b32_e32 v140, v142
	v_permlane16_swap_b32_e32 v141, v143
	global_store_dwordx4 v[172:173], v[140:143], off offset:64
	v_pk_mul_f32 v[14:15], v[14:15], v[156:157] op_sel_hi:[1,0]
	v_pk_mul_f32 v[16:17], v[16:17], v[156:157] op_sel_hi:[1,0]
	v_pk_mul_f32 v[10:11], v[10:11], v[156:157] op_sel_hi:[1,0]
	v_pk_mul_f32 v[12:13], v[12:13], v[156:157] op_sel_hi:[1,0]
	v_pk_mul_f32 v[6:7], v[6:7], v[156:157] op_sel_hi:[1,0]
	v_pk_mul_f32 v[8:9], v[8:9], v[156:157] op_sel_hi:[1,0]
	v_pk_mul_f32 v[2:3], v[2:3], v[156:157] op_sel_hi:[1,0]
	v_pk_mul_f32 v[4:5], v[4:5], v[156:157] op_sel_hi:[1,0]
	global_store_dwordx4 v[164:165], v[14:17], off offset:512
	global_store_dwordx4 v[164:165], v[10:13], off offset:576
	global_store_dwordx4 v[164:165], v[6:9], off offset:640
	global_store_dwordx4 v[164:165], v[2:5], off offset:704
	v_cvt_pk_bf16_f32 v130, v14, v15
	v_cvt_pk_bf16_f32 v131, v16, v17
	v_cvt_pk_bf16_f32 v132, v10, v11
	v_cvt_pk_bf16_f32 v133, v12, v13
	s_nop 1
	v_permlane16_swap_b32_e32 v130, v132
	v_permlane16_swap_b32_e32 v131, v133
	global_store_dwordx4 v[172:173], v[130:133], off offset:256
	v_cvt_pk_bf16_f32 v140, v6, v7
	v_cvt_pk_bf16_f32 v141, v8, v9
	v_cvt_pk_bf16_f32 v142, v2, v3
	v_cvt_pk_bf16_f32 v143, v4, v5
	s_nop 1
	v_permlane16_swap_b32_e32 v140, v142
	v_permlane16_swap_b32_e32 v141, v143
	global_store_dwordx4 v[172:173], v[140:143], off offset:320
	s_branch .Lmy_qkv_done
; __device__ __forceinline__ uint32_t pack2(float a, float b) { return (uint32_t)f2bf(a) | ((uint32_t)f2bf(b) << 16); }
;     ...
;           if (cls < 2) {
;             float ss = 0.f;
;             for (int m = 0; m < 4; ++m) for (int jj = 0; jj < 4; ++jj) { const float t = acc[ai][bj][m][nn][jj] * rs; ss += t * t; }
;             ss += __shfl_xor(ss, 16); ss += __shfl_xor(ss, 32);
;             hr = rsqrtf(ss * (1.f / 64.f) + EPS) * sc;
;           }
;           for (int m = 0; m < 4; ++m) {
;             const int n = nb + ai * HALF + wr * 64 + m * 16 + efq * 4;
;             float4 g4 = make_float4(1.f, 1.f, 1.f, 1.f);
;             if (cls < 2) g4 = *(const float4*)(gp + m * 16 + efq * 4);
;             const float o0 = acc[ai][bj][m][nn][0] * rs * hr * g4.x, o1 = acc[ai][bj][m][nn][1] * rs * hr * g4.y;
;             const float o2 = acc[ai][bj][m][nn][2] * rs * hr * g4.z, o3 = acc[ai][bj][m][nn][3] * rs * hr * g4.w;
;             uint2 pk; pk.x = pack2(o0, o1); pk.y = pack2(o2, o3);
;             if (cls == 0) { *(uint2*)(Qn + tok * DM + n) = pk; }
.Lmy_qkv_q:
	v_pk_mul_f32 v[126:127], v[126:127], v[150:151] op_sel_hi:[1,0]
	v_pk_mul_f32 v[128:129], v[128:129], v[150:151] op_sel_hi:[1,0]
	v_pk_mul_f32 v[122:123], v[122:123], v[150:151] op_sel_hi:[1,0]
	v_pk_mul_f32 v[124:125], v[124:125], v[150:151] op_sel_hi:[1,0]
	v_pk_mul_f32 v[118:119], v[118:119], v[150:151] op_sel_hi:[1,0]
	v_pk_mul_f32 v[120:121], v[120:121], v[150:151] op_sel_hi:[1,0]
	v_pk_mul_f32 v[114:115], v[114:115], v[150:151] op_sel_hi:[1,0]
	v_pk_mul_f32 v[116:117], v[116:117], v[150:151] op_sel_hi:[1,0]
	v_mul_f32_e32 v176, v126, v126
	v_fmac_f32_e32 v176, v127, v127
	v_fmac_f32_e32 v176, v128, v128
	v_fmac_f32_e32 v176, v129, v129
	v_fmac_f32_e32 v176, v122, v122
	v_fmac_f32_e32 v176, v123, v123
	v_fmac_f32_e32 v176, v124, v124
	v_fmac_f32_e32 v176, v125, v125
	v_fmac_f32_e32 v176, v118, v118
	v_fmac_f32_e32 v176, v119, v119
	v_fmac_f32_e32 v176, v120, v120
	v_fmac_f32_e32 v176, v121, v121
	v_fmac_f32_e32 v176, v114, v114
	v_fmac_f32_e32 v176, v115, v115
	v_fmac_f32_e32 v176, v116, v116
	v_fmac_f32_e32 v176, v117, v117
	ds_bpermute_b32 v177, v135, v176
	s_waitcnt lgkmcnt(0)
	v_add_f32_e32 v176, v176, v177
	ds_bpermute_b32 v177, v136, v176
	s_waitcnt lgkmcnt(0)
	v_add_f32_e32 v176, v176, v177
	v_fmamk_f32 v176, v176, 0x3c800000, v137
	v_rsq_f32_e32 v174, v176
	s_nop 0
	v_mul_f32_e32 v174, 0x3e38aa3b, v174
	v_pk_mul_f32 v[126:127], v[126:127], v[174:175] op_sel_hi:[1,0]
	v_pk_mul_f32 v[128:129], v[128:129], v[174:175] op_sel_hi:[1,0]
	v_pk_mul_f32 v[122:123], v[122:123], v[174:175] op_sel_hi:[1,0]
	v_pk_mul_f32 v[124:125], v[124:125], v[174:175] op_sel_hi:[1,0]
	v_pk_mul_f32 v[118:119], v[118:119], v[174:175] op_sel_hi:[1,0]
	v_pk_mul_f32 v[120:121], v[120:121], v[174:175] op_sel_hi:[1,0]
	v_pk_mul_f32 v[114:115], v[114:115], v[174:175] op_sel_hi:[1,0]
	v_pk_mul_f32 v[116:117], v[116:117], v[174:175] op_sel_hi:[1,0]
	v_pk_mul_f32 v[126:127], v[126:127], v[182:183]
	v_pk_mul_f32 v[128:129], v[128:129], v[184:185]
	v_pk_mul_f32 v[122:123], v[122:123], v[186:187]
	v_pk_mul_f32 v[124:125], v[124:125], v[188:189]
	v_pk_mul_f32 v[118:119], v[118:119], v[190:191]
	v_pk_mul_f32 v[120:121], v[120:121], v[192:193]
	v_pk_mul_f32 v[114:115], v[114:115], v[194:195]
	v_pk_mul_f32 v[116:117], v[116:117], v[196:197]
	v_cvt_pk_bf16_f32 v130, v126, v127
	v_cvt_pk_bf16_f32 v131, v128, v129
	v_cvt_pk_bf16_f32 v132, v122, v123
	v_cvt_pk_bf16_f32 v133, v124, v125
	s_nop 1
	v_permlane16_swap_b32_e32 v130, v132
	v_permlane16_swap_b32_e32 v131, v133
	global_store_dwordx4 v[166:167], v[130:133], off
	v_cvt_pk_bf16_f32 v140, v118, v119
	v_cvt_pk_bf16_f32 v141, v120, v121
	v_cvt_pk_bf16_f32 v142, v114, v115
	v_cvt_pk_bf16_f32 v143, v116, v117
	s_nop 1
	v_permlane16_swap_b32_e32 v140, v142
	v_permlane16_swap_b32_e32 v141, v143
	global_store_dwordx4 v[166:167], v[140:143], off offset:64
	v_pk_mul_f32 v[110:111], v[110:111], v[150:151] op_sel_hi:[1,0]
	v_pk_mul_f32 v[112:113], v[112:113], v[150:151] op_sel_hi:[1,0]
	v_pk_mul_f32 v[106:107], v[106:107], v[150:151] op_sel_hi:[1,0]
	v_pk_mul_f32 v[108:109], v[108:109], v[150:151] op_sel_hi:[1,0]
	v_pk_mul_f32 v[102:103], v[102:103], v[150:151] op_sel_hi:[1,0]
	v_pk_mul_f32 v[104:105], v[104:105], v[150:151] op_sel_hi:[1,0]
	v_pk_mul_f32 v[98:99], v[98:99], v[150:151] op_sel_hi:[1,0]
	v_pk_mul_f32 v[100:101], v[100:101], v[150:151] op_sel_hi:[1,0]
	v_mul_f32_e32 v176, v110, v110
	v_fmac_f32_e32 v176, v111, v111
	v_fmac_f32_e32 v176, v112, v112
	v_fmac_f32_e32 v176, v113, v113
	v_fmac_f32_e32 v176, v106, v106
	v_fmac_f32_e32 v176, v107, v107
	v_fmac_f32_e32 v176, v108, v108
	v_fmac_f32_e32 v176, v109, v109
	v_fmac_f32_e32 v176, v102, v102
	v_fmac_f32_e32 v176, v103, v103
	v_fmac_f32_e32 v176, v104, v104
	v_fmac_f32_e32 v176, v105, v105
	v_fmac_f32_e32 v176, v98, v98
	v_fmac_f32_e32 v176, v99, v99
	v_fmac_f32_e32 v176, v100, v100
	v_fmac_f32_e32 v176, v101, v101
	ds_bpermute_b32 v177, v135, v176
	s_waitcnt lgkmcnt(0)
	v_add_f32_e32 v176, v176, v177
	ds_bpermute_b32 v177, v136, v176
	s_waitcnt lgkmcnt(0)
	v_add_f32_e32 v176, v176, v177
	v_fmamk_f32 v176, v176, 0x3c800000, v137
	v_rsq_f32_e32 v174, v176
	s_nop 0
	v_mul_f32_e32 v174, 0x3e38aa3b, v174
	v_pk_mul_f32 v[110:111], v[110:111], v[174:175] op_sel_hi:[1,0]
	v_pk_mul_f32 v[112:113], v[112:113], v[174:175] op_sel_hi:[1,0]
	v_pk_mul_f32 v[106:107], v[106:107], v[174:175] op_sel_hi:[1,0]
	v_pk_mul_f32 v[108:109], v[108:109], v[174:175] op_sel_hi:[1,0]
	v_pk_mul_f32 v[102:103], v[102:103], v[174:175] op_sel_hi:[1,0]
	v_pk_mul_f32 v[104:105], v[104:105], v[174:175] op_sel_hi:[1,0]
	v_pk_mul_f32 v[98:99], v[98:99], v[174:175] op_sel_hi:[1,0]
	v_pk_mul_f32 v[100:101], v[100:101], v[174:175] op_sel_hi:[1,0]
	v_pk_mul_f32 v[110:111], v[110:111], v[182:183]
	v_pk_mul_f32 v[112:113], v[112:113], v[184:185]
	v_pk_mul_f32 v[106:107], v[106:107], v[186:187]
	v_pk_mul_f32 v[108:109], v[108:109], v[188:189]
	v_pk_mul_f32 v[102:103], v[102:103], v[190:191]
	v_pk_mul_f32 v[104:105], v[104:105], v[192:193]
	v_pk_mul_f32 v[98:99], v[98:99], v[194:195]
	v_pk_mul_f32 v[100:101], v[100:101], v[196:197]
	v_cvt_pk_bf16_f32 v130, v110, v111
	v_cvt_pk_bf16_f32 v131, v112, v113
	v_cvt_pk_bf16_f32 v132, v106, v107
	v_cvt_pk_bf16_f32 v133, v108, v109
	s_nop 1
	v_permlane16_swap_b32_e32 v130, v132
	v_permlane16_swap_b32_e32 v131, v133
	global_store_dwordx4 v[166:167], v[130:133], off offset:256
	v_cvt_pk_bf16_f32 v140, v102, v103
	v_cvt_pk_bf16_f32 v141, v104, v105
	v_cvt_pk_bf16_f32 v142, v98, v99
	v_cvt_pk_bf16_f32 v143, v100, v101
	s_nop 1
	v_permlane16_swap_b32_e32 v140, v142
	v_permlane16_swap_b32_e32 v141, v143
	global_store_dwordx4 v[166:167], v[140:143], off offset:320
	v_pk_mul_f32 v[94:95], v[94:95], v[152:153] op_sel_hi:[1,0]
	v_pk_mul_f32 v[96:97], v[96:97], v[152:153] op_sel_hi:[1,0]
	v_pk_mul_f32 v[90:91], v[90:91], v[152:153] op_sel_hi:[1,0]
	v_pk_mul_f32 v[92:93], v[92:93], v[152:153] op_sel_hi:[1,0]
	v_pk_mul_f32 v[86:87], v[86:87], v[152:153] op_sel_hi:[1,0]
	v_pk_mul_f32 v[88:89], v[88:89], v[152:153] op_sel_hi:[1,0]
	v_pk_mul_f32 v[82:83], v[82:83], v[152:153] op_sel_hi:[1,0]
	v_pk_mul_f32 v[84:85], v[84:85], v[152:153] op_sel_hi:[1,0]
	v_mul_f32_e32 v176, v94, v94
	v_fmac_f32_e32 v176, v95, v95
	v_fmac_f32_e32 v176, v96, v96
	v_fmac_f32_e32 v176, v97, v97
	v_fmac_f32_e32 v176, v90, v90
	v_fmac_f32_e32 v176, v91, v91
	v_fmac_f32_e32 v176, v92, v92
	v_fmac_f32_e32 v176, v93, v93
	v_fmac_f32_e32 v176, v86, v86
	v_fmac_f32_e32 v176, v87, v87
	v_fmac_f32_e32 v176, v88, v88
	v_fmac_f32_e32 v176, v89, v89
	v_fmac_f32_e32 v176, v82, v82
	v_fmac_f32_e32 v176, v83, v83
	v_fmac_f32_e32 v176, v84, v84
	v_fmac_f32_e32 v176, v85, v85
	ds_bpermute_b32 v177, v135, v176
	s_waitcnt lgkmcnt(0)
; __device__ __forceinline__ uint32_t pack2(float a, float b) { return (uint32_t)f2bf(a) | ((uint32_t)f2bf(b) << 16); }
;     ...
;           if (cls < 2) {
;             float ss = 0.f;
;             for (int m = 0; m < 4; ++m) for (int jj = 0; jj < 4; ++jj) { const float t = acc[ai][bj][m][nn][jj] * rs; ss += t * t; }
;             ss += __shfl_xor(ss, 16); ss += __shfl_xor(ss, 32);
;             hr = rsqrtf(ss * (1.f / 64.f) + EPS) * sc;
;           }
;           for (int m = 0; m < 4; ++m) {
;             const int n = nb + ai * HALF + wr * 64 + m * 16 + efq * 4;
;             float4 g4 = make_float4(1.f, 1.f, 1.f, 1.f);
;             if (cls < 2) g4 = *(const float4*)(gp + m * 16 + efq * 4);
;             const float o0 = acc[ai][bj][m][nn][0] * rs * hr * g4.x, o1 = acc[ai][bj][m][nn][1] * rs * hr * g4.y;
;             const float o2 = acc[ai][bj][m][nn][2] * rs * hr * g4.z, o3 = acc[ai][bj][m][nn][3] * rs * hr * g4.w;
;             uint2 pk; pk.x = pack2(o0, o1); pk.y = pack2(o2, o3);
;             if (cls == 0) { *(uint2*)(Qn + tok * DM + n) = pk; }
	v_add_f32_e32 v176, v176, v177
	ds_bpermute_b32 v177, v136, v176
	s_waitcnt lgkmcnt(0)
	v_add_f32_e32 v176, v176, v177
	v_fmamk_f32 v176, v176, 0x3c800000, v137
	v_rsq_f32_e32 v174, v176
	s_nop 0
	v_mul_f32_e32 v174, 0x3e38aa3b, v174
	v_pk_mul_f32 v[94:95], v[94:95], v[174:175] op_sel_hi:[1,0]
	v_pk_mul_f32 v[96:97], v[96:97], v[174:175] op_sel_hi:[1,0]
	v_pk_mul_f32 v[90:91], v[90:91], v[174:175] op_sel_hi:[1,0]
	v_pk_mul_f32 v[92:93], v[92:93], v[174:175] op_sel_hi:[1,0]
	v_pk_mul_f32 v[86:87], v[86:87], v[174:175] op_sel_hi:[1,0]
	v_pk_mul_f32 v[88:89], v[88:89], v[174:175] op_sel_hi:[1,0]
	v_pk_mul_f32 v[82:83], v[82:83], v[174:175] op_sel_hi:[1,0]
	v_pk_mul_f32 v[84:85], v[84:85], v[174:175] op_sel_hi:[1,0]
	v_pk_mul_f32 v[94:95], v[94:95], v[182:183]
	v_pk_mul_f32 v[96:97], v[96:97], v[184:185]
	v_pk_mul_f32 v[90:91], v[90:91], v[186:187]
	v_pk_mul_f32 v[92:93], v[92:93], v[188:189]
	v_pk_mul_f32 v[86:87], v[86:87], v[190:191]
	v_pk_mul_f32 v[88:89], v[88:89], v[192:193]
	v_pk_mul_f32 v[82:83], v[82:83], v[194:195]
	v_pk_mul_f32 v[84:85], v[84:85], v[196:197]
	v_cvt_pk_bf16_f32 v130, v94, v95
	v_cvt_pk_bf16_f32 v131, v96, v97
	v_cvt_pk_bf16_f32 v132, v90, v91
	v_cvt_pk_bf16_f32 v133, v92, v93
	s_nop 1
	v_permlane16_swap_b32_e32 v130, v132
	v_permlane16_swap_b32_e32 v131, v133
	global_store_dwordx4 v[168:169], v[130:133], off
	v_cvt_pk_bf16_f32 v140, v86, v87
	v_cvt_pk_bf16_f32 v141, v88, v89
	v_cvt_pk_bf16_f32 v142, v82, v83
	v_cvt_pk_bf16_f32 v143, v84, v85
	s_nop 1
	v_permlane16_swap_b32_e32 v140, v142
	v_permlane16_swap_b32_e32 v141, v143
	global_store_dwordx4 v[168:169], v[140:143], off offset:64
	v_pk_mul_f32 v[78:79], v[78:79], v[152:153] op_sel_hi:[1,0]
	v_pk_mul_f32 v[80:81], v[80:81], v[152:153] op_sel_hi:[1,0]
	v_pk_mul_f32 v[74:75], v[74:75], v[152:153] op_sel_hi:[1,0]
	v_pk_mul_f32 v[76:77], v[76:77], v[152:153] op_sel_hi:[1,0]
	v_pk_mul_f32 v[70:71], v[70:71], v[152:153] op_sel_hi:[1,0]
	v_pk_mul_f32 v[72:73], v[72:73], v[152:153] op_sel_hi:[1,0]
	v_pk_mul_f32 v[66:67], v[66:67], v[152:153] op_sel_hi:[1,0]
	v_pk_mul_f32 v[68:69], v[68:69], v[152:153] op_sel_hi:[1,0]
	v_mul_f32_e32 v176, v78, v78
	v_fmac_f32_e32 v176, v79, v79
	v_fmac_f32_e32 v176, v80, v80
	v_fmac_f32_e32 v176, v81, v81
	v_fmac_f32_e32 v176, v74, v74
	v_fmac_f32_e32 v176, v75, v75
	v_fmac_f32_e32 v176, v76, v76
	v_fmac_f32_e32 v176, v77, v77
	v_fmac_f32_e32 v176, v70, v70
	v_fmac_f32_e32 v176, v71, v71
	v_fmac_f32_e32 v176, v72, v72
	v_fmac_f32_e32 v176, v73, v73
	v_fmac_f32_e32 v176, v66, v66
	v_fmac_f32_e32 v176, v67, v67
	v_fmac_f32_e32 v176, v68, v68
	v_fmac_f32_e32 v176, v69, v69
	ds_bpermute_b32 v177, v135, v176
	s_waitcnt lgkmcnt(0)
	v_add_f32_e32 v176, v176, v177
	ds_bpermute_b32 v177, v136, v176
	s_waitcnt lgkmcnt(0)
	v_add_f32_e32 v176, v176, v177
	v_fmamk_f32 v176, v176, 0x3c800000, v137
	v_rsq_f32_e32 v174, v176
	s_nop 0
	v_mul_f32_e32 v174, 0x3e38aa3b, v174
	v_pk_mul_f32 v[78:79], v[78:79], v[174:175] op_sel_hi:[1,0]
	v_pk_mul_f32 v[80:81], v[80:81], v[174:175] op_sel_hi:[1,0]
	v_pk_mul_f32 v[74:75], v[74:75], v[174:175] op_sel_hi:[1,0]
	v_pk_mul_f32 v[76:77], v[76:77], v[174:175] op_sel_hi:[1,0]
	v_pk_mul_f32 v[70:71], v[70:71], v[174:175] op_sel_hi:[1,0]
	v_pk_mul_f32 v[72:73], v[72:73], v[174:175] op_sel_hi:[1,0]
	v_pk_mul_f32 v[66:67], v[66:67], v[174:175] op_sel_hi:[1,0]
	v_pk_mul_f32 v[68:69], v[68:69], v[174:175] op_sel_hi:[1,0]
	v_pk_mul_f32 v[78:79], v[78:79], v[182:183]
	v_pk_mul_f32 v[80:81], v[80:81], v[184:185]
	v_pk_mul_f32 v[74:75], v[74:75], v[186:187]
	v_pk_mul_f32 v[76:77], v[76:77], v[188:189]
	v_pk_mul_f32 v[70:71], v[70:71], v[190:191]
	v_pk_mul_f32 v[72:73], v[72:73], v[192:193]
	v_pk_mul_f32 v[66:67], v[66:67], v[194:195]
	v_pk_mul_f32 v[68:69], v[68:69], v[196:197]
	v_cvt_pk_bf16_f32 v130, v78, v79
	v_cvt_pk_bf16_f32 v131, v80, v81
	v_cvt_pk_bf16_f32 v132, v74, v75
	v_cvt_pk_bf16_f32 v133, v76, v77
	s_nop 1
	v_permlane16_swap_b32_e32 v130, v132
	v_permlane16_swap_b32_e32 v131, v133
	global_store_dwordx4 v[168:169], v[130:133], off offset:256
	v_cvt_pk_bf16_f32 v140, v70, v71
	v_cvt_pk_bf16_f32 v141, v72, v73
	v_cvt_pk_bf16_f32 v142, v66, v67
	v_cvt_pk_bf16_f32 v143, v68, v69
	s_nop 1
	v_permlane16_swap_b32_e32 v140, v142
	v_permlane16_swap_b32_e32 v141, v143
	global_store_dwordx4 v[168:169], v[140:143], off offset:320
	v_pk_mul_f32 v[62:63], v[62:63], v[154:155] op_sel_hi:[1,0]
	v_pk_mul_f32 v[64:65], v[64:65], v[154:155] op_sel_hi:[1,0]
	v_pk_mul_f32 v[58:59], v[58:59], v[154:155] op_sel_hi:[1,0]
	v_pk_mul_f32 v[60:61], v[60:61], v[154:155] op_sel_hi:[1,0]
	v_pk_mul_f32 v[54:55], v[54:55], v[154:155] op_sel_hi:[1,0]
	v_pk_mul_f32 v[56:57], v[56:57], v[154:155] op_sel_hi:[1,0]
	v_pk_mul_f32 v[50:51], v[50:51], v[154:155] op_sel_hi:[1,0]
	v_pk_mul_f32 v[52:53], v[52:53], v[154:155] op_sel_hi:[1,0]
	v_mul_f32_e32 v176, v62, v62
	v_fmac_f32_e32 v176, v63, v63
	v_fmac_f32_e32 v176, v64, v64
	v_fmac_f32_e32 v176, v65, v65
	v_fmac_f32_e32 v176, v58, v58
	v_fmac_f32_e32 v176, v59, v59
	v_fmac_f32_e32 v176, v60, v60
	v_fmac_f32_e32 v176, v61, v61
	v_fmac_f32_e32 v176, v54, v54
	v_fmac_f32_e32 v176, v55, v55
	v_fmac_f32_e32 v176, v56, v56
	v_fmac_f32_e32 v176, v57, v57
	v_fmac_f32_e32 v176, v50, v50
	v_fmac_f32_e32 v176, v51, v51
	v_fmac_f32_e32 v176, v52, v52
	v_fmac_f32_e32 v176, v53, v53
	ds_bpermute_b32 v177, v135, v176
	s_waitcnt lgkmcnt(0)
	v_add_f32_e32 v176, v176, v177
	ds_bpermute_b32 v177, v136, v176
	s_waitcnt lgkmcnt(0)
; __device__ __forceinline__ uint32_t pack2(float a, float b) { return (uint32_t)f2bf(a) | ((uint32_t)f2bf(b) << 16); }
;     ...
;           if (cls < 2) {
;             float ss = 0.f;
;             for (int m = 0; m < 4; ++m) for (int jj = 0; jj < 4; ++jj) { const float t = acc[ai][bj][m][nn][jj] * rs; ss += t * t; }
;             ss += __shfl_xor(ss, 16); ss += __shfl_xor(ss, 32);
;             hr = rsqrtf(ss * (1.f / 64.f) + EPS) * sc;
;           }
;           for (int m = 0; m < 4; ++m) {
;             const int n = nb + ai * HALF + wr * 64 + m * 16 + efq * 4;
;             float4 g4 = make_float4(1.f, 1.f, 1.f, 1.f);
;             if (cls < 2) g4 = *(const float4*)(gp + m * 16 + efq * 4);
;             const float o0 = acc[ai][bj][m][nn][0] * rs * hr * g4.x, o1 = acc[ai][bj][m][nn][1] * rs * hr * g4.y;
;             const float o2 = acc[ai][bj][m][nn][2] * rs * hr * g4.z, o3 = acc[ai][bj][m][nn][3] * rs * hr * g4.w;
;             uint2 pk; pk.x = pack2(o0, o1); pk.y = pack2(o2, o3);
;             if (cls == 0) { *(uint2*)(Qn + tok * DM + n) = pk; }
	v_add_f32_e32 v176, v176, v177
	v_fmamk_f32 v176, v176, 0x3c800000, v137
	v_rsq_f32_e32 v174, v176
	s_nop 0
	v_mul_f32_e32 v174, 0x3e38aa3b, v174
	v_pk_mul_f32 v[62:63], v[62:63], v[174:175] op_sel_hi:[1,0]
	v_pk_mul_f32 v[64:65], v[64:65], v[174:175] op_sel_hi:[1,0]
	v_pk_mul_f32 v[58:59], v[58:59], v[174:175] op_sel_hi:[1,0]
	v_pk_mul_f32 v[60:61], v[60:61], v[174:175] op_sel_hi:[1,0]
	v_pk_mul_f32 v[54:55], v[54:55], v[174:175] op_sel_hi:[1,0]
	v_pk_mul_f32 v[56:57], v[56:57], v[174:175] op_sel_hi:[1,0]
	v_pk_mul_f32 v[50:51], v[50:51], v[174:175] op_sel_hi:[1,0]
	v_pk_mul_f32 v[52:53], v[52:53], v[174:175] op_sel_hi:[1,0]
	v_pk_mul_f32 v[62:63], v[62:63], v[182:183]
	v_pk_mul_f32 v[64:65], v[64:65], v[184:185]
	v_pk_mul_f32 v[58:59], v[58:59], v[186:187]
	v_pk_mul_f32 v[60:61], v[60:61], v[188:189]
	v_pk_mul_f32 v[54:55], v[54:55], v[190:191]
	v_pk_mul_f32 v[56:57], v[56:57], v[192:193]
	v_pk_mul_f32 v[50:51], v[50:51], v[194:195]
	v_pk_mul_f32 v[52:53], v[52:53], v[196:197]
	v_cvt_pk_bf16_f32 v130, v62, v63
	v_cvt_pk_bf16_f32 v131, v64, v65
	v_cvt_pk_bf16_f32 v132, v58, v59
	v_cvt_pk_bf16_f32 v133, v60, v61
	s_nop 1
	v_permlane16_swap_b32_e32 v130, v132
	v_permlane16_swap_b32_e32 v131, v133
	global_store_dwordx4 v[170:171], v[130:133], off
	v_cvt_pk_bf16_f32 v140, v54, v55
	v_cvt_pk_bf16_f32 v141, v56, v57
	v_cvt_pk_bf16_f32 v142, v50, v51
	v_cvt_pk_bf16_f32 v143, v52, v53
	s_nop 1
	v_permlane16_swap_b32_e32 v140, v142
	v_permlane16_swap_b32_e32 v141, v143
	global_store_dwordx4 v[170:171], v[140:143], off offset:64
	v_pk_mul_f32 v[46:47], v[46:47], v[154:155] op_sel_hi:[1,0]
	v_pk_mul_f32 v[48:49], v[48:49], v[154:155] op_sel_hi:[1,0]
	v_pk_mul_f32 v[42:43], v[42:43], v[154:155] op_sel_hi:[1,0]
	v_pk_mul_f32 v[44:45], v[44:45], v[154:155] op_sel_hi:[1,0]
	v_pk_mul_f32 v[38:39], v[38:39], v[154:155] op_sel_hi:[1,0]
	v_pk_mul_f32 v[40:41], v[40:41], v[154:155] op_sel_hi:[1,0]
	v_pk_mul_f32 v[34:35], v[34:35], v[154:155] op_sel_hi:[1,0]
	v_pk_mul_f32 v[36:37], v[36:37], v[154:155] op_sel_hi:[1,0]
	v_mul_f32_e32 v176, v46, v46
	v_fmac_f32_e32 v176, v47, v47
	v_fmac_f32_e32 v176, v48, v48
	v_fmac_f32_e32 v176, v49, v49
	v_fmac_f32_e32 v176, v42, v42
	v_fmac_f32_e32 v176, v43, v43
	v_fmac_f32_e32 v176, v44, v44
	v_fmac_f32_e32 v176, v45, v45
	v_fmac_f32_e32 v176, v38, v38
	v_fmac_f32_e32 v176, v39, v39
	v_fmac_f32_e32 v176, v40, v40
	v_fmac_f32_e32 v176, v41, v41
	v_fmac_f32_e32 v176, v34, v34
	v_fmac_f32_e32 v176, v35, v35
	v_fmac_f32_e32 v176, v36, v36
	v_fmac_f32_e32 v176, v37, v37
	ds_bpermute_b32 v177, v135, v176
	s_waitcnt lgkmcnt(0)
	v_add_f32_e32 v176, v176, v177
	ds_bpermute_b32 v177, v136, v176
	s_waitcnt lgkmcnt(0)
	v_add_f32_e32 v176, v176, v177
	v_fmamk_f32 v176, v176, 0x3c800000, v137
	v_rsq_f32_e32 v174, v176
	s_nop 0
	v_mul_f32_e32 v174, 0x3e38aa3b, v174
	v_pk_mul_f32 v[46:47], v[46:47], v[174:175] op_sel_hi:[1,0]
	v_pk_mul_f32 v[48:49], v[48:49], v[174:175] op_sel_hi:[1,0]
	v_pk_mul_f32 v[42:43], v[42:43], v[174:175] op_sel_hi:[1,0]
	v_pk_mul_f32 v[44:45], v[44:45], v[174:175] op_sel_hi:[1,0]
	v_pk_mul_f32 v[38:39], v[38:39], v[174:175] op_sel_hi:[1,0]
	v_pk_mul_f32 v[40:41], v[40:41], v[174:175] op_sel_hi:[1,0]
	v_pk_mul_f32 v[34:35], v[34:35], v[174:175] op_sel_hi:[1,0]
	v_pk_mul_f32 v[36:37], v[36:37], v[174:175] op_sel_hi:[1,0]
	v_pk_mul_f32 v[46:47], v[46:47], v[182:183]
	v_pk_mul_f32 v[48:49], v[48:49], v[184:185]
	v_pk_mul_f32 v[42:43], v[42:43], v[186:187]
	v_pk_mul_f32 v[44:45], v[44:45], v[188:189]
	v_pk_mul_f32 v[38:39], v[38:39], v[190:191]
	v_pk_mul_f32 v[40:41], v[40:41], v[192:193]
	v_pk_mul_f32 v[34:35], v[34:35], v[194:195]
	v_pk_mul_f32 v[36:37], v[36:37], v[196:197]
	v_cvt_pk_bf16_f32 v130, v46, v47
	v_cvt_pk_bf16_f32 v131, v48, v49
	v_cvt_pk_bf16_f32 v132, v42, v43
	v_cvt_pk_bf16_f32 v133, v44, v45
	s_nop 1
	v_permlane16_swap_b32_e32 v130, v132
	v_permlane16_swap_b32_e32 v131, v133
	global_store_dwordx4 v[170:171], v[130:133], off offset:256
	v_cvt_pk_bf16_f32 v140, v38, v39
	v_cvt_pk_bf16_f32 v141, v40, v41
	v_cvt_pk_bf16_f32 v142, v34, v35
	v_cvt_pk_bf16_f32 v143, v36, v37
	s_nop 1
	v_permlane16_swap_b32_e32 v140, v142
	v_permlane16_swap_b32_e32 v141, v143
	global_store_dwordx4 v[170:171], v[140:143], off offset:320
	v_pk_mul_f32 v[30:31], v[30:31], v[156:157] op_sel_hi:[1,0]
	v_pk_mul_f32 v[32:33], v[32:33], v[156:157] op_sel_hi:[1,0]
	v_pk_mul_f32 v[26:27], v[26:27], v[156:157] op_sel_hi:[1,0]
	v_pk_mul_f32 v[28:29], v[28:29], v[156:157] op_sel_hi:[1,0]
	v_pk_mul_f32 v[22:23], v[22:23], v[156:157] op_sel_hi:[1,0]
	v_pk_mul_f32 v[24:25], v[24:25], v[156:157] op_sel_hi:[1,0]
	v_pk_mul_f32 v[18:19], v[18:19], v[156:157] op_sel_hi:[1,0]
	v_pk_mul_f32 v[20:21], v[20:21], v[156:157] op_sel_hi:[1,0]
	v_mul_f32_e32 v176, v30, v30
	v_fmac_f32_e32 v176, v31, v31
	v_fmac_f32_e32 v176, v32, v32
	v_fmac_f32_e32 v176, v33, v33
	v_fmac_f32_e32 v176, v26, v26
	v_fmac_f32_e32 v176, v27, v27
	v_fmac_f32_e32 v176, v28, v28
	v_fmac_f32_e32 v176, v29, v29
	v_fmac_f32_e32 v176, v22, v22
	v_fmac_f32_e32 v176, v23, v23
	v_fmac_f32_e32 v176, v24, v24
	v_fmac_f32_e32 v176, v25, v25
	v_fmac_f32_e32 v176, v18, v18
	v_fmac_f32_e32 v176, v19, v19
	v_fmac_f32_e32 v176, v20, v20
	v_fmac_f32_e32 v176, v21, v21
	ds_bpermute_b32 v177, v135, v176
	s_waitcnt lgkmcnt(0)
	v_add_f32_e32 v176, v176, v177
	ds_bpermute_b32 v177, v136, v176
	s_waitcnt lgkmcnt(0)
; __device__ __forceinline__ uint32_t pack2(float a, float b) { return (uint32_t)f2bf(a) | ((uint32_t)f2bf(b) << 16); }
;     ...
;           if (cls < 2) {
;             float ss = 0.f;
;             for (int m = 0; m < 4; ++m) for (int jj = 0; jj < 4; ++jj) { const float t = acc[ai][bj][m][nn][jj] * rs; ss += t * t; }
;             ss += __shfl_xor(ss, 16); ss += __shfl_xor(ss, 32);
;             hr = rsqrtf(ss * (1.f / 64.f) + EPS) * sc;
;           }
;           for (int m = 0; m < 4; ++m) {
;             const int n = nb + ai * HALF + wr * 64 + m * 16 + efq * 4;
;             float4 g4 = make_float4(1.f, 1.f, 1.f, 1.f);
;             if (cls < 2) g4 = *(const float4*)(gp + m * 16 + efq * 4);
;             const float o0 = acc[ai][bj][m][nn][0] * rs * hr * g4.x, o1 = acc[ai][bj][m][nn][1] * rs * hr * g4.y;
;             const float o2 = acc[ai][bj][m][nn][2] * rs * hr * g4.z, o3 = acc[ai][bj][m][nn][3] * rs * hr * g4.w;
;             uint2 pk; pk.x = pack2(o0, o1); pk.y = pack2(o2, o3);
;             if (cls == 0) { *(uint2*)(Qn + tok * DM + n) = pk; }
;             else {
;               float* of = pq->out + (cls == 1 ? (prompt ? O_PK + ((long)jq * TP + tok) * DM : O_SK + ((long)jq * TS + (tok - TP)) * DM)
;                                               : (prompt ? O_PV + ((long)jq * TP + tok) * DM : O_SV + ((long)jq * TS + (tok - TP)) * DM)) + n;
;               *(float4*)of = make_float4(o0, o1, o2, o3);
;               if (prompt) {
;                 if (cls == 1) *(uint2*)(Kn + tok * DM + n) = pk;
	v_add_f32_e32 v176, v176, v177
	v_fmamk_f32 v176, v176, 0x3c800000, v137
	v_rsq_f32_e32 v174, v176
	s_nop 0
	v_mul_f32_e32 v174, 0x3e38aa3b, v174
	v_pk_mul_f32 v[30:31], v[30:31], v[174:175] op_sel_hi:[1,0]
	v_pk_mul_f32 v[32:33], v[32:33], v[174:175] op_sel_hi:[1,0]
	v_pk_mul_f32 v[26:27], v[26:27], v[174:175] op_sel_hi:[1,0]
	v_pk_mul_f32 v[28:29], v[28:29], v[174:175] op_sel_hi:[1,0]
	v_pk_mul_f32 v[22:23], v[22:23], v[174:175] op_sel_hi:[1,0]
	v_pk_mul_f32 v[24:25], v[24:25], v[174:175] op_sel_hi:[1,0]
	v_pk_mul_f32 v[18:19], v[18:19], v[174:175] op_sel_hi:[1,0]
	v_pk_mul_f32 v[20:21], v[20:21], v[174:175] op_sel_hi:[1,0]
	v_pk_mul_f32 v[30:31], v[30:31], v[182:183]
	v_pk_mul_f32 v[32:33], v[32:33], v[184:185]
	v_pk_mul_f32 v[26:27], v[26:27], v[186:187]
	v_pk_mul_f32 v[28:29], v[28:29], v[188:189]
	v_pk_mul_f32 v[22:23], v[22:23], v[190:191]
	v_pk_mul_f32 v[24:25], v[24:25], v[192:193]
	v_pk_mul_f32 v[18:19], v[18:19], v[194:195]
	v_pk_mul_f32 v[20:21], v[20:21], v[196:197]
	v_cvt_pk_bf16_f32 v130, v30, v31
	v_cvt_pk_bf16_f32 v131, v32, v33
	v_cvt_pk_bf16_f32 v132, v26, v27
	v_cvt_pk_bf16_f32 v133, v28, v29
	s_nop 1
	v_permlane16_swap_b32_e32 v130, v132
	v_permlane16_swap_b32_e32 v131, v133
	global_store_dwordx4 v[172:173], v[130:133], off
	v_cvt_pk_bf16_f32 v140, v22, v23
	v_cvt_pk_bf16_f32 v141, v24, v25
	v_cvt_pk_bf16_f32 v142, v18, v19
	v_cvt_pk_bf16_f32 v143, v20, v21
	s_nop 1
	v_permlane16_swap_b32_e32 v140, v142
	v_permlane16_swap_b32_e32 v141, v143
	global_store_dwordx4 v[172:173], v[140:143], off offset:64
	v_pk_mul_f32 v[14:15], v[14:15], v[156:157] op_sel_hi:[1,0]
	v_pk_mul_f32 v[16:17], v[16:17], v[156:157] op_sel_hi:[1,0]
	v_pk_mul_f32 v[10:11], v[10:11], v[156:157] op_sel_hi:[1,0]
	v_pk_mul_f32 v[12:13], v[12:13], v[156:157] op_sel_hi:[1,0]
	v_pk_mul_f32 v[6:7], v[6:7], v[156:157] op_sel_hi:[1,0]
	v_pk_mul_f32 v[8:9], v[8:9], v[156:157] op_sel_hi:[1,0]
	v_pk_mul_f32 v[2:3], v[2:3], v[156:157] op_sel_hi:[1,0]
	v_pk_mul_f32 v[4:5], v[4:5], v[156:157] op_sel_hi:[1,0]
	v_mul_f32_e32 v176, v14, v14
	v_fmac_f32_e32 v176, v15, v15
	v_fmac_f32_e32 v176, v16, v16
	v_fmac_f32_e32 v176, v17, v17
	v_fmac_f32_e32 v176, v10, v10
	v_fmac_f32_e32 v176, v11, v11
	v_fmac_f32_e32 v176, v12, v12
	v_fmac_f32_e32 v176, v13, v13
	v_fmac_f32_e32 v176, v6, v6
	v_fmac_f32_e32 v176, v7, v7
	v_fmac_f32_e32 v176, v8, v8
	v_fmac_f32_e32 v176, v9, v9
	v_fmac_f32_e32 v176, v2, v2
	v_fmac_f32_e32 v176, v3, v3
	v_fmac_f32_e32 v176, v4, v4
	v_fmac_f32_e32 v176, v5, v5
	ds_bpermute_b32 v177, v135, v176
	s_waitcnt lgkmcnt(0)
	v_add_f32_e32 v176, v176, v177
	ds_bpermute_b32 v177, v136, v176
	s_waitcnt lgkmcnt(0)
	v_add_f32_e32 v176, v176, v177
	v_fmamk_f32 v176, v176, 0x3c800000, v137
	v_rsq_f32_e32 v174, v176
	s_nop 0
	v_mul_f32_e32 v174, 0x3e38aa3b, v174
	v_pk_mul_f32 v[14:15], v[14:15], v[174:175] op_sel_hi:[1,0]
	v_pk_mul_f32 v[16:17], v[16:17], v[174:175] op_sel_hi:[1,0]
	v_pk_mul_f32 v[10:11], v[10:11], v[174:175] op_sel_hi:[1,0]
	v_pk_mul_f32 v[12:13], v[12:13], v[174:175] op_sel_hi:[1,0]
	v_pk_mul_f32 v[6:7], v[6:7], v[174:175] op_sel_hi:[1,0]
	v_pk_mul_f32 v[8:9], v[8:9], v[174:175] op_sel_hi:[1,0]
	v_pk_mul_f32 v[2:3], v[2:3], v[174:175] op_sel_hi:[1,0]
	v_pk_mul_f32 v[4:5], v[4:5], v[174:175] op_sel_hi:[1,0]
	v_pk_mul_f32 v[14:15], v[14:15], v[182:183]
	v_pk_mul_f32 v[16:17], v[16:17], v[184:185]
	v_pk_mul_f32 v[10:11], v[10:11], v[186:187]
	v_pk_mul_f32 v[12:13], v[12:13], v[188:189]
	v_pk_mul_f32 v[6:7], v[6:7], v[190:191]
	v_pk_mul_f32 v[8:9], v[8:9], v[192:193]
	v_pk_mul_f32 v[2:3], v[2:3], v[194:195]
	v_pk_mul_f32 v[4:5], v[4:5], v[196:197]
	v_cvt_pk_bf16_f32 v130, v14, v15
	v_cvt_pk_bf16_f32 v131, v16, v17
	v_cvt_pk_bf16_f32 v132, v10, v11
	v_cvt_pk_bf16_f32 v133, v12, v13
	s_nop 1
	v_permlane16_swap_b32_e32 v130, v132
	v_permlane16_swap_b32_e32 v131, v133
	global_store_dwordx4 v[172:173], v[130:133], off offset:256
	v_cvt_pk_bf16_f32 v140, v6, v7
	v_cvt_pk_bf16_f32 v141, v8, v9
	v_cvt_pk_bf16_f32 v142, v2, v3
	v_cvt_pk_bf16_f32 v143, v4, v5
	s_nop 1
	v_permlane16_swap_b32_e32 v140, v142
	v_permlane16_swap_b32_e32 v141, v143
	global_store_dwordx4 v[172:173], v[140:143], off offset:320
	s_branch .Lmy_qkv_done
.Lmy_qkv_k:
	v_pk_mul_f32 v[126:127], v[126:127], v[150:151] op_sel_hi:[1,0]
	v_pk_mul_f32 v[128:129], v[128:129], v[150:151] op_sel_hi:[1,0]
	v_pk_mul_f32 v[122:123], v[122:123], v[150:151] op_sel_hi:[1,0]
	v_pk_mul_f32 v[124:125], v[124:125], v[150:151] op_sel_hi:[1,0]
	v_pk_mul_f32 v[118:119], v[118:119], v[150:151] op_sel_hi:[1,0]
	v_pk_mul_f32 v[120:121], v[120:121], v[150:151] op_sel_hi:[1,0]
	v_pk_mul_f32 v[114:115], v[114:115], v[150:151] op_sel_hi:[1,0]
	v_pk_mul_f32 v[116:117], v[116:117], v[150:151] op_sel_hi:[1,0]
	v_mul_f32_e32 v176, v126, v126
	v_fmac_f32_e32 v176, v127, v127
	v_fmac_f32_e32 v176, v128, v128
	v_fmac_f32_e32 v176, v129, v129
	v_fmac_f32_e32 v176, v122, v122
	v_fmac_f32_e32 v176, v123, v123
	v_fmac_f32_e32 v176, v124, v124
	v_fmac_f32_e32 v176, v125, v125
	v_fmac_f32_e32 v176, v118, v118
	v_fmac_f32_e32 v176, v119, v119
	v_fmac_f32_e32 v176, v120, v120
	v_fmac_f32_e32 v176, v121, v121
	v_fmac_f32_e32 v176, v114, v114
	v_fmac_f32_e32 v176, v115, v115
	v_fmac_f32_e32 v176, v116, v116
	v_fmac_f32_e32 v176, v117, v117
	ds_bpermute_b32 v177, v135, v176
	s_waitcnt lgkmcnt(0)
	v_add_f32_e32 v176, v176, v177
	ds_bpermute_b32 v177, v136, v176
	s_waitcnt lgkmcnt(0)
; __device__ __forceinline__ uint32_t pack2(float a, float b) { return (uint32_t)f2bf(a) | ((uint32_t)f2bf(b) << 16); }
;     ...
;           if (cls < 2) {
;             float ss = 0.f;
;             for (int m = 0; m < 4; ++m) for (int jj = 0; jj < 4; ++jj) { const float t = acc[ai][bj][m][nn][jj] * rs; ss += t * t; }
;             ss += __shfl_xor(ss, 16); ss += __shfl_xor(ss, 32);
;             hr = rsqrtf(ss * (1.f / 64.f) + EPS) * sc;
;           }
;           for (int m = 0; m < 4; ++m) {
;             const int n = nb + ai * HALF + wr * 64 + m * 16 + efq * 4;
;             float4 g4 = make_float4(1.f, 1.f, 1.f, 1.f);
;             if (cls < 2) g4 = *(const float4*)(gp + m * 16 + efq * 4);
;             const float o0 = acc[ai][bj][m][nn][0] * rs * hr * g4.x, o1 = acc[ai][bj][m][nn][1] * rs * hr * g4.y;
;             const float o2 = acc[ai][bj][m][nn][2] * rs * hr * g4.z, o3 = acc[ai][bj][m][nn][3] * rs * hr * g4.w;
;             uint2 pk; pk.x = pack2(o0, o1); pk.y = pack2(o2, o3);
;             if (cls == 0) { *(uint2*)(Qn + tok * DM + n) = pk; }
;             else {
;               float* of = pq->out + (cls == 1 ? (prompt ? O_PK + ((long)jq * TP + tok) * DM : O_SK + ((long)jq * TS + (tok - TP)) * DM)
;                                               : (prompt ? O_PV + ((long)jq * TP + tok) * DM : O_SV + ((long)jq * TS + (tok - TP)) * DM)) + n;
;               *(float4*)of = make_float4(o0, o1, o2, o3);
;               if (prompt) {
;                 if (cls == 1) *(uint2*)(Kn + tok * DM + n) = pk;
	v_add_f32_e32 v176, v176, v177
	v_fmamk_f32 v176, v176, 0x3c800000, v137
	v_rsq_f32_e32 v174, v176
	s_nop 0
	v_pk_mul_f32 v[126:127], v[126:127], v[174:175] op_sel_hi:[1,0]
	v_pk_mul_f32 v[128:129], v[128:129], v[174:175] op_sel_hi:[1,0]
	v_pk_mul_f32 v[122:123], v[122:123], v[174:175] op_sel_hi:[1,0]
	v_pk_mul_f32 v[124:125], v[124:125], v[174:175] op_sel_hi:[1,0]
	v_pk_mul_f32 v[118:119], v[118:119], v[174:175] op_sel_hi:[1,0]
	v_pk_mul_f32 v[120:121], v[120:121], v[174:175] op_sel_hi:[1,0]
	v_pk_mul_f32 v[114:115], v[114:115], v[174:175] op_sel_hi:[1,0]
	v_pk_mul_f32 v[116:117], v[116:117], v[174:175] op_sel_hi:[1,0]
	v_pk_mul_f32 v[126:127], v[126:127], v[182:183]
	v_pk_mul_f32 v[128:129], v[128:129], v[184:185]
	v_pk_mul_f32 v[122:123], v[122:123], v[186:187]
	v_pk_mul_f32 v[124:125], v[124:125], v[188:189]
	v_pk_mul_f32 v[118:119], v[118:119], v[190:191]
	v_pk_mul_f32 v[120:121], v[120:121], v[192:193]
	v_pk_mul_f32 v[114:115], v[114:115], v[194:195]
	v_pk_mul_f32 v[116:117], v[116:117], v[196:197]
	global_store_dwordx4 v[158:159], v[126:129], off
	global_store_dwordx4 v[158:159], v[122:125], off offset:64
	global_store_dwordx4 v[158:159], v[118:121], off offset:128
	global_store_dwordx4 v[158:159], v[114:117], off offset:192
	v_cvt_pk_bf16_f32 v130, v126, v127
	v_cvt_pk_bf16_f32 v131, v128, v129
	v_cvt_pk_bf16_f32 v132, v122, v123
	v_cvt_pk_bf16_f32 v133, v124, v125
	s_nop 1
	v_permlane16_swap_b32_e32 v130, v132
	v_permlane16_swap_b32_e32 v131, v133
	global_store_dwordx4 v[166:167], v[130:133], off
	v_cvt_pk_bf16_f32 v140, v118, v119
	v_cvt_pk_bf16_f32 v141, v120, v121
	v_cvt_pk_bf16_f32 v142, v114, v115
	v_cvt_pk_bf16_f32 v143, v116, v117
	s_nop 1
	v_permlane16_swap_b32_e32 v140, v142
	v_permlane16_swap_b32_e32 v141, v143
	global_store_dwordx4 v[166:167], v[140:143], off offset:64
	v_pk_mul_f32 v[110:111], v[110:111], v[150:151] op_sel_hi:[1,0]
	v_pk_mul_f32 v[112:113], v[112:113], v[150:151] op_sel_hi:[1,0]
	v_pk_mul_f32 v[106:107], v[106:107], v[150:151] op_sel_hi:[1,0]
	v_pk_mul_f32 v[108:109], v[108:109], v[150:151] op_sel_hi:[1,0]
	v_pk_mul_f32 v[102:103], v[102:103], v[150:151] op_sel_hi:[1,0]
	v_pk_mul_f32 v[104:105], v[104:105], v[150:151] op_sel_hi:[1,0]
	v_pk_mul_f32 v[98:99], v[98:99], v[150:151] op_sel_hi:[1,0]
	v_pk_mul_f32 v[100:101], v[100:101], v[150:151] op_sel_hi:[1,0]
	v_mul_f32_e32 v176, v110, v110
	v_fmac_f32_e32 v176, v111, v111
	v_fmac_f32_e32 v176, v112, v112
	v_fmac_f32_e32 v176, v113, v113
	v_fmac_f32_e32 v176, v106, v106
	v_fmac_f32_e32 v176, v107, v107
	v_fmac_f32_e32 v176, v108, v108
	v_fmac_f32_e32 v176, v109, v109
	v_fmac_f32_e32 v176, v102, v102
	v_fmac_f32_e32 v176, v103, v103
	v_fmac_f32_e32 v176, v104, v104
	v_fmac_f32_e32 v176, v105, v105
	v_fmac_f32_e32 v176, v98, v98
	v_fmac_f32_e32 v176, v99, v99
	v_fmac_f32_e32 v176, v100, v100
	v_fmac_f32_e32 v176, v101, v101
	ds_bpermute_b32 v177, v135, v176
	s_waitcnt lgkmcnt(0)
	v_add_f32_e32 v176, v176, v177
	ds_bpermute_b32 v177, v136, v176
	s_waitcnt lgkmcnt(0)
	v_add_f32_e32 v176, v176, v177
	v_fmamk_f32 v176, v176, 0x3c800000, v137
	v_rsq_f32_e32 v174, v176
	s_nop 0
	v_pk_mul_f32 v[110:111], v[110:111], v[174:175] op_sel_hi:[1,0]
	v_pk_mul_f32 v[112:113], v[112:113], v[174:175] op_sel_hi:[1,0]
	v_pk_mul_f32 v[106:107], v[106:107], v[174:175] op_sel_hi:[1,0]
	v_pk_mul_f32 v[108:109], v[108:109], v[174:175] op_sel_hi:[1,0]
	v_pk_mul_f32 v[102:103], v[102:103], v[174:175] op_sel_hi:[1,0]
	v_pk_mul_f32 v[104:105], v[104:105], v[174:175] op_sel_hi:[1,0]
	v_pk_mul_f32 v[98:99], v[98:99], v[174:175] op_sel_hi:[1,0]
	v_pk_mul_f32 v[100:101], v[100:101], v[174:175] op_sel_hi:[1,0]
	v_pk_mul_f32 v[110:111], v[110:111], v[182:183]
	v_pk_mul_f32 v[112:113], v[112:113], v[184:185]
	v_pk_mul_f32 v[106:107], v[106:107], v[186:187]
	v_pk_mul_f32 v[108:109], v[108:109], v[188:189]
	v_pk_mul_f32 v[102:103], v[102:103], v[190:191]
	v_pk_mul_f32 v[104:105], v[104:105], v[192:193]
	v_pk_mul_f32 v[98:99], v[98:99], v[194:195]
	v_pk_mul_f32 v[100:101], v[100:101], v[196:197]
	global_store_dwordx4 v[158:159], v[110:113], off offset:512
	global_store_dwordx4 v[158:159], v[106:109], off offset:576
	global_store_dwordx4 v[158:159], v[102:105], off offset:640
	global_store_dwordx4 v[158:159], v[98:101], off offset:704
	v_cvt_pk_bf16_f32 v130, v110, v111
	v_cvt_pk_bf16_f32 v131, v112, v113
	v_cvt_pk_bf16_f32 v132, v106, v107
	v_cvt_pk_bf16_f32 v133, v108, v109
	s_nop 1
	v_permlane16_swap_b32_e32 v130, v132
	v_permlane16_swap_b32_e32 v131, v133
	global_store_dwordx4 v[166:167], v[130:133], off offset:256
	v_cvt_pk_bf16_f32 v140, v102, v103
	v_cvt_pk_bf16_f32 v141, v104, v105
	v_cvt_pk_bf16_f32 v142, v98, v99
	v_cvt_pk_bf16_f32 v143, v100, v101
	s_nop 1
	v_permlane16_swap_b32_e32 v140, v142
	v_permlane16_swap_b32_e32 v141, v143
	global_store_dwordx4 v[166:167], v[140:143], off offset:320
	v_pk_mul_f32 v[94:95], v[94:95], v[152:153] op_sel_hi:[1,0]
	v_pk_mul_f32 v[96:97], v[96:97], v[152:153] op_sel_hi:[1,0]
	v_pk_mul_f32 v[90:91], v[90:91], v[152:153] op_sel_hi:[1,0]
	v_pk_mul_f32 v[92:93], v[92:93], v[152:153] op_sel_hi:[1,0]
	v_pk_mul_f32 v[86:87], v[86:87], v[152:153] op_sel_hi:[1,0]
	v_pk_mul_f32 v[88:89], v[88:89], v[152:153] op_sel_hi:[1,0]
	v_pk_mul_f32 v[82:83], v[82:83], v[152:153] op_sel_hi:[1,0]
	v_pk_mul_f32 v[84:85], v[84:85], v[152:153] op_sel_hi:[1,0]
	v_mul_f32_e32 v176, v94, v94
	v_fmac_f32_e32 v176, v95, v95
	v_fmac_f32_e32 v176, v96, v96
	v_fmac_f32_e32 v176, v97, v97
	v_fmac_f32_e32 v176, v90, v90
	v_fmac_f32_e32 v176, v91, v91
	v_fmac_f32_e32 v176, v92, v92
	v_fmac_f32_e32 v176, v93, v93
	v_fmac_f32_e32 v176, v86, v86
	v_fmac_f32_e32 v176, v87, v87
	v_fmac_f32_e32 v176, v88, v88
	v_fmac_f32_e32 v176, v89, v89
	v_fmac_f32_e32 v176, v82, v82
	v_fmac_f32_e32 v176, v83, v83
	v_fmac_f32_e32 v176, v84, v84
	v_fmac_f32_e32 v176, v85, v85
	ds_bpermute_b32 v177, v135, v176
	s_waitcnt lgkmcnt(0)
; __device__ __forceinline__ uint32_t pack2(float a, float b) { return (uint32_t)f2bf(a) | ((uint32_t)f2bf(b) << 16); }
;     ...
;           if (cls < 2) {
;             float ss = 0.f;
;             for (int m = 0; m < 4; ++m) for (int jj = 0; jj < 4; ++jj) { const float t = acc[ai][bj][m][nn][jj] * rs; ss += t * t; }
;             ss += __shfl_xor(ss, 16); ss += __shfl_xor(ss, 32);
;             hr = rsqrtf(ss * (1.f / 64.f) + EPS) * sc;
;           }
;           for (int m = 0; m < 4; ++m) {
;             const int n = nb + ai * HALF + wr * 64 + m * 16 + efq * 4;
;             float4 g4 = make_float4(1.f, 1.f, 1.f, 1.f);
;             if (cls < 2) g4 = *(const float4*)(gp + m * 16 + efq * 4);
;             const float o0 = acc[ai][bj][m][nn][0] * rs * hr * g4.x, o1 = acc[ai][bj][m][nn][1] * rs * hr * g4.y;
;             const float o2 = acc[ai][bj][m][nn][2] * rs * hr * g4.z, o3 = acc[ai][bj][m][nn][3] * rs * hr * g4.w;
;             uint2 pk; pk.x = pack2(o0, o1); pk.y = pack2(o2, o3);
;             if (cls == 0) { *(uint2*)(Qn + tok * DM + n) = pk; }
;             else {
;               float* of = pq->out + (cls == 1 ? (prompt ? O_PK + ((long)jq * TP + tok) * DM : O_SK + ((long)jq * TS + (tok - TP)) * DM)
;                                               : (prompt ? O_PV + ((long)jq * TP + tok) * DM : O_SV + ((long)jq * TS + (tok - TP)) * DM)) + n;
;               *(float4*)of = make_float4(o0, o1, o2, o3);
;               if (prompt) {
;                 if (cls == 1) *(uint2*)(Kn + tok * DM + n) = pk;
	v_add_f32_e32 v176, v176, v177
	ds_bpermute_b32 v177, v136, v176
	s_waitcnt lgkmcnt(0)
	v_add_f32_e32 v176, v176, v177
	v_fmamk_f32 v176, v176, 0x3c800000, v137
	v_rsq_f32_e32 v174, v176
	s_nop 0
	v_pk_mul_f32 v[94:95], v[94:95], v[174:175] op_sel_hi:[1,0]
	v_pk_mul_f32 v[96:97], v[96:97], v[174:175] op_sel_hi:[1,0]
	v_pk_mul_f32 v[90:91], v[90:91], v[174:175] op_sel_hi:[1,0]
	v_pk_mul_f32 v[92:93], v[92:93], v[174:175] op_sel_hi:[1,0]
	v_pk_mul_f32 v[86:87], v[86:87], v[174:175] op_sel_hi:[1,0]
	v_pk_mul_f32 v[88:89], v[88:89], v[174:175] op_sel_hi:[1,0]
	v_pk_mul_f32 v[82:83], v[82:83], v[174:175] op_sel_hi:[1,0]
	v_pk_mul_f32 v[84:85], v[84:85], v[174:175] op_sel_hi:[1,0]
	v_pk_mul_f32 v[94:95], v[94:95], v[182:183]
	v_pk_mul_f32 v[96:97], v[96:97], v[184:185]
	v_pk_mul_f32 v[90:91], v[90:91], v[186:187]
	v_pk_mul_f32 v[92:93], v[92:93], v[188:189]
	v_pk_mul_f32 v[86:87], v[86:87], v[190:191]
	v_pk_mul_f32 v[88:89], v[88:89], v[192:193]
	v_pk_mul_f32 v[82:83], v[82:83], v[194:195]
	v_pk_mul_f32 v[84:85], v[84:85], v[196:197]
	global_store_dwordx4 v[160:161], v[94:97], off
	global_store_dwordx4 v[160:161], v[90:93], off offset:64
	global_store_dwordx4 v[160:161], v[86:89], off offset:128
	global_store_dwordx4 v[160:161], v[82:85], off offset:192
	v_cvt_pk_bf16_f32 v130, v94, v95
	v_cvt_pk_bf16_f32 v131, v96, v97
	v_cvt_pk_bf16_f32 v132, v90, v91
	v_cvt_pk_bf16_f32 v133, v92, v93
	s_nop 1
	v_permlane16_swap_b32_e32 v130, v132
	v_permlane16_swap_b32_e32 v131, v133
	global_store_dwordx4 v[168:169], v[130:133], off
	v_cvt_pk_bf16_f32 v140, v86, v87
	v_cvt_pk_bf16_f32 v141, v88, v89
	v_cvt_pk_bf16_f32 v142, v82, v83
	v_cvt_pk_bf16_f32 v143, v84, v85
	s_nop 1
	v_permlane16_swap_b32_e32 v140, v142
	v_permlane16_swap_b32_e32 v141, v143
	global_store_dwordx4 v[168:169], v[140:143], off offset:64
	v_pk_mul_f32 v[78:79], v[78:79], v[152:153] op_sel_hi:[1,0]
	v_pk_mul_f32 v[80:81], v[80:81], v[152:153] op_sel_hi:[1,0]
	v_pk_mul_f32 v[74:75], v[74:75], v[152:153] op_sel_hi:[1,0]
	v_pk_mul_f32 v[76:77], v[76:77], v[152:153] op_sel_hi:[1,0]
	v_pk_mul_f32 v[70:71], v[70:71], v[152:153] op_sel_hi:[1,0]
	v_pk_mul_f32 v[72:73], v[72:73], v[152:153] op_sel_hi:[1,0]
	v_pk_mul_f32 v[66:67], v[66:67], v[152:153] op_sel_hi:[1,0]
	v_pk_mul_f32 v[68:69], v[68:69], v[152:153] op_sel_hi:[1,0]
	v_mul_f32_e32 v176, v78, v78
	v_fmac_f32_e32 v176, v79, v79
	v_fmac_f32_e32 v176, v80, v80
	v_fmac_f32_e32 v176, v81, v81
	v_fmac_f32_e32 v176, v74, v74
	v_fmac_f32_e32 v176, v75, v75
	v_fmac_f32_e32 v176, v76, v76
	v_fmac_f32_e32 v176, v77, v77
	v_fmac_f32_e32 v176, v70, v70
	v_fmac_f32_e32 v176, v71, v71
	v_fmac_f32_e32 v176, v72, v72
	v_fmac_f32_e32 v176, v73, v73
	v_fmac_f32_e32 v176, v66, v66
	v_fmac_f32_e32 v176, v67, v67
	v_fmac_f32_e32 v176, v68, v68
	v_fmac_f32_e32 v176, v69, v69
	ds_bpermute_b32 v177, v135, v176
	s_waitcnt lgkmcnt(0)
	v_add_f32_e32 v176, v176, v177
	ds_bpermute_b32 v177, v136, v176
	s_waitcnt lgkmcnt(0)
	v_add_f32_e32 v176, v176, v177
	v_fmamk_f32 v176, v176, 0x3c800000, v137
	v_rsq_f32_e32 v174, v176
	s_nop 0
	v_pk_mul_f32 v[78:79], v[78:79], v[174:175] op_sel_hi:[1,0]
	v_pk_mul_f32 v[80:81], v[80:81], v[174:175] op_sel_hi:[1,0]
	v_pk_mul_f32 v[74:75], v[74:75], v[174:175] op_sel_hi:[1,0]
	v_pk_mul_f32 v[76:77], v[76:77], v[174:175] op_sel_hi:[1,0]
	v_pk_mul_f32 v[70:71], v[70:71], v[174:175] op_sel_hi:[1,0]
	v_pk_mul_f32 v[72:73], v[72:73], v[174:175] op_sel_hi:[1,0]
	v_pk_mul_f32 v[66:67], v[66:67], v[174:175] op_sel_hi:[1,0]
	v_pk_mul_f32 v[68:69], v[68:69], v[174:175] op_sel_hi:[1,0]
	v_pk_mul_f32 v[78:79], v[78:79], v[182:183]
	v_pk_mul_f32 v[80:81], v[80:81], v[184:185]
	v_pk_mul_f32 v[74:75], v[74:75], v[186:187]
	v_pk_mul_f32 v[76:77], v[76:77], v[188:189]
	v_pk_mul_f32 v[70:71], v[70:71], v[190:191]
	v_pk_mul_f32 v[72:73], v[72:73], v[192:193]
	v_pk_mul_f32 v[66:67], v[66:67], v[194:195]
	v_pk_mul_f32 v[68:69], v[68:69], v[196:197]
	global_store_dwordx4 v[160:161], v[78:81], off offset:512
	global_store_dwordx4 v[160:161], v[74:77], off offset:576
	global_store_dwordx4 v[160:161], v[70:73], off offset:640
	global_store_dwordx4 v[160:161], v[66:69], off offset:704
	v_cvt_pk_bf16_f32 v130, v78, v79
	v_cvt_pk_bf16_f32 v131, v80, v81
	v_cvt_pk_bf16_f32 v132, v74, v75
	v_cvt_pk_bf16_f32 v133, v76, v77
	s_nop 1
	v_permlane16_swap_b32_e32 v130, v132
	v_permlane16_swap_b32_e32 v131, v133
	global_store_dwordx4 v[168:169], v[130:133], off offset:256
	v_cvt_pk_bf16_f32 v140, v70, v71
	v_cvt_pk_bf16_f32 v141, v72, v73
	v_cvt_pk_bf16_f32 v142, v66, v67
	v_cvt_pk_bf16_f32 v143, v68, v69
	s_nop 1
	v_permlane16_swap_b32_e32 v140, v142
	v_permlane16_swap_b32_e32 v141, v143
	global_store_dwordx4 v[168:169], v[140:143], off offset:320
	v_pk_mul_f32 v[62:63], v[62:63], v[154:155] op_sel_hi:[1,0]
	v_pk_mul_f32 v[64:65], v[64:65], v[154:155] op_sel_hi:[1,0]
	v_pk_mul_f32 v[58:59], v[58:59], v[154:155] op_sel_hi:[1,0]
	v_pk_mul_f32 v[60:61], v[60:61], v[154:155] op_sel_hi:[1,0]
	v_pk_mul_f32 v[54:55], v[54:55], v[154:155] op_sel_hi:[1,0]
	v_pk_mul_f32 v[56:57], v[56:57], v[154:155] op_sel_hi:[1,0]
	v_pk_mul_f32 v[50:51], v[50:51], v[154:155] op_sel_hi:[1,0]
	v_pk_mul_f32 v[52:53], v[52:53], v[154:155] op_sel_hi:[1,0]
	v_mul_f32_e32 v176, v62, v62
	v_fmac_f32_e32 v176, v63, v63
	v_fmac_f32_e32 v176, v64, v64
	v_fmac_f32_e32 v176, v65, v65
	v_fmac_f32_e32 v176, v58, v58
	v_fmac_f32_e32 v176, v59, v59
	v_fmac_f32_e32 v176, v60, v60
	v_fmac_f32_e32 v176, v61, v61
	v_fmac_f32_e32 v176, v54, v54
	v_fmac_f32_e32 v176, v55, v55
	v_fmac_f32_e32 v176, v56, v56
	v_fmac_f32_e32 v176, v57, v57
	v_fmac_f32_e32 v176, v50, v50
	v_fmac_f32_e32 v176, v51, v51
	v_fmac_f32_e32 v176, v52, v52
	v_fmac_f32_e32 v176, v53, v53
	ds_bpermute_b32 v177, v135, v176
	s_waitcnt lgkmcnt(0)
; __device__ __forceinline__ uint32_t pack2(float a, float b) { return (uint32_t)f2bf(a) | ((uint32_t)f2bf(b) << 16); }
;     ...
;           if (cls < 2) {
;             float ss = 0.f;
;             for (int m = 0; m < 4; ++m) for (int jj = 0; jj < 4; ++jj) { const float t = acc[ai][bj][m][nn][jj] * rs; ss += t * t; }
;             ss += __shfl_xor(ss, 16); ss += __shfl_xor(ss, 32);
;             hr = rsqrtf(ss * (1.f / 64.f) + EPS) * sc;
;           }
;           for (int m = 0; m < 4; ++m) {
;             const int n = nb + ai * HALF + wr * 64 + m * 16 + efq * 4;
;             float4 g4 = make_float4(1.f, 1.f, 1.f, 1.f);
;             if (cls < 2) g4 = *(const float4*)(gp + m * 16 + efq * 4);
;             const float o0 = acc[ai][bj][m][nn][0] * rs * hr * g4.x, o1 = acc[ai][bj][m][nn][1] * rs * hr * g4.y;
;             const float o2 = acc[ai][bj][m][nn][2] * rs * hr * g4.z, o3 = acc[ai][bj][m][nn][3] * rs * hr * g4.w;
;             uint2 pk; pk.x = pack2(o0, o1); pk.y = pack2(o2, o3);
;             if (cls == 0) { *(uint2*)(Qn + tok * DM + n) = pk; }
;             else {
;               float* of = pq->out + (cls == 1 ? (prompt ? O_PK + ((long)jq * TP + tok) * DM : O_SK + ((long)jq * TS + (tok - TP)) * DM)
;                                               : (prompt ? O_PV + ((long)jq * TP + tok) * DM : O_SV + ((long)jq * TS + (tok - TP)) * DM)) + n;
;               *(float4*)of = make_float4(o0, o1, o2, o3);
;               if (prompt) {
;                 if (cls == 1) *(uint2*)(Kn + tok * DM + n) = pk;
	v_add_f32_e32 v176, v176, v177
	ds_bpermute_b32 v177, v136, v176
	s_waitcnt lgkmcnt(0)
	v_add_f32_e32 v176, v176, v177
	v_fmamk_f32 v176, v176, 0x3c800000, v137
	v_rsq_f32_e32 v174, v176
	s_nop 0
	v_pk_mul_f32 v[62:63], v[62:63], v[174:175] op_sel_hi:[1,0]
	v_pk_mul_f32 v[64:65], v[64:65], v[174:175] op_sel_hi:[1,0]
	v_pk_mul_f32 v[58:59], v[58:59], v[174:175] op_sel_hi:[1,0]
	v_pk_mul_f32 v[60:61], v[60:61], v[174:175] op_sel_hi:[1,0]
	v_pk_mul_f32 v[54:55], v[54:55], v[174:175] op_sel_hi:[1,0]
	v_pk_mul_f32 v[56:57], v[56:57], v[174:175] op_sel_hi:[1,0]
	v_pk_mul_f32 v[50:51], v[50:51], v[174:175] op_sel_hi:[1,0]
	v_pk_mul_f32 v[52:53], v[52:53], v[174:175] op_sel_hi:[1,0]
	v_pk_mul_f32 v[62:63], v[62:63], v[182:183]
	v_pk_mul_f32 v[64:65], v[64:65], v[184:185]
	v_pk_mul_f32 v[58:59], v[58:59], v[186:187]
	v_pk_mul_f32 v[60:61], v[60:61], v[188:189]
	v_pk_mul_f32 v[54:55], v[54:55], v[190:191]
	v_pk_mul_f32 v[56:57], v[56:57], v[192:193]
	v_pk_mul_f32 v[50:51], v[50:51], v[194:195]
	v_pk_mul_f32 v[52:53], v[52:53], v[196:197]
	global_store_dwordx4 v[162:163], v[62:65], off
	global_store_dwordx4 v[162:163], v[58:61], off offset:64
	global_store_dwordx4 v[162:163], v[54:57], off offset:128
	global_store_dwordx4 v[162:163], v[50:53], off offset:192
	v_cvt_pk_bf16_f32 v130, v62, v63
	v_cvt_pk_bf16_f32 v131, v64, v65
	v_cvt_pk_bf16_f32 v132, v58, v59
	v_cvt_pk_bf16_f32 v133, v60, v61
	s_nop 1
	v_permlane16_swap_b32_e32 v130, v132
	v_permlane16_swap_b32_e32 v131, v133
	global_store_dwordx4 v[170:171], v[130:133], off
	v_cvt_pk_bf16_f32 v140, v54, v55
	v_cvt_pk_bf16_f32 v141, v56, v57
	v_cvt_pk_bf16_f32 v142, v50, v51
	v_cvt_pk_bf16_f32 v143, v52, v53
	s_nop 1
	v_permlane16_swap_b32_e32 v140, v142
	v_permlane16_swap_b32_e32 v141, v143
	global_store_dwordx4 v[170:171], v[140:143], off offset:64
	v_pk_mul_f32 v[46:47], v[46:47], v[154:155] op_sel_hi:[1,0]
	v_pk_mul_f32 v[48:49], v[48:49], v[154:155] op_sel_hi:[1,0]
	v_pk_mul_f32 v[42:43], v[42:43], v[154:155] op_sel_hi:[1,0]
	v_pk_mul_f32 v[44:45], v[44:45], v[154:155] op_sel_hi:[1,0]
	v_pk_mul_f32 v[38:39], v[38:39], v[154:155] op_sel_hi:[1,0]
	v_pk_mul_f32 v[40:41], v[40:41], v[154:155] op_sel_hi:[1,0]
	v_pk_mul_f32 v[34:35], v[34:35], v[154:155] op_sel_hi:[1,0]
	v_pk_mul_f32 v[36:37], v[36:37], v[154:155] op_sel_hi:[1,0]
	v_mul_f32_e32 v176, v46, v46
	v_fmac_f32_e32 v176, v47, v47
	v_fmac_f32_e32 v176, v48, v48
	v_fmac_f32_e32 v176, v49, v49
	v_fmac_f32_e32 v176, v42, v42
	v_fmac_f32_e32 v176, v43, v43
	v_fmac_f32_e32 v176, v44, v44
	v_fmac_f32_e32 v176, v45, v45
	v_fmac_f32_e32 v176, v38, v38
	v_fmac_f32_e32 v176, v39, v39
	v_fmac_f32_e32 v176, v40, v40
	v_fmac_f32_e32 v176, v41, v41
	v_fmac_f32_e32 v176, v34, v34
	v_fmac_f32_e32 v176, v35, v35
	v_fmac_f32_e32 v176, v36, v36
	v_fmac_f32_e32 v176, v37, v37
	ds_bpermute_b32 v177, v135, v176
	s_waitcnt lgkmcnt(0)
	v_add_f32_e32 v176, v176, v177
	ds_bpermute_b32 v177, v136, v176
	s_waitcnt lgkmcnt(0)
	v_add_f32_e32 v176, v176, v177
	v_fmamk_f32 v176, v176, 0x3c800000, v137
	v_rsq_f32_e32 v174, v176
	s_nop 0
	v_pk_mul_f32 v[46:47], v[46:47], v[174:175] op_sel_hi:[1,0]
	v_pk_mul_f32 v[48:49], v[48:49], v[174:175] op_sel_hi:[1,0]
	v_pk_mul_f32 v[42:43], v[42:43], v[174:175] op_sel_hi:[1,0]
	v_pk_mul_f32 v[44:45], v[44:45], v[174:175] op_sel_hi:[1,0]
	v_pk_mul_f32 v[38:39], v[38:39], v[174:175] op_sel_hi:[1,0]
	v_pk_mul_f32 v[40:41], v[40:41], v[174:175] op_sel_hi:[1,0]
	v_pk_mul_f32 v[34:35], v[34:35], v[174:175] op_sel_hi:[1,0]
	v_pk_mul_f32 v[36:37], v[36:37], v[174:175] op_sel_hi:[1,0]
	v_pk_mul_f32 v[46:47], v[46:47], v[182:183]
	v_pk_mul_f32 v[48:49], v[48:49], v[184:185]
	v_pk_mul_f32 v[42:43], v[42:43], v[186:187]
	v_pk_mul_f32 v[44:45], v[44:45], v[188:189]
	v_pk_mul_f32 v[38:39], v[38:39], v[190:191]
	v_pk_mul_f32 v[40:41], v[40:41], v[192:193]
	v_pk_mul_f32 v[34:35], v[34:35], v[194:195]
	v_pk_mul_f32 v[36:37], v[36:37], v[196:197]
	global_store_dwordx4 v[162:163], v[46:49], off offset:512
	global_store_dwordx4 v[162:163], v[42:45], off offset:576
	global_store_dwordx4 v[162:163], v[38:41], off offset:640
	global_store_dwordx4 v[162:163], v[34:37], off offset:704
	v_cvt_pk_bf16_f32 v130, v46, v47
	v_cvt_pk_bf16_f32 v131, v48, v49
	v_cvt_pk_bf16_f32 v132, v42, v43
	v_cvt_pk_bf16_f32 v133, v44, v45
	s_nop 1
	v_permlane16_swap_b32_e32 v130, v132
	v_permlane16_swap_b32_e32 v131, v133
	global_store_dwordx4 v[170:171], v[130:133], off offset:256
	v_cvt_pk_bf16_f32 v140, v38, v39
	v_cvt_pk_bf16_f32 v141, v40, v41
	v_cvt_pk_bf16_f32 v142, v34, v35
	v_cvt_pk_bf16_f32 v143, v36, v37
	s_nop 1
	v_permlane16_swap_b32_e32 v140, v142
	v_permlane16_swap_b32_e32 v141, v143
	global_store_dwordx4 v[170:171], v[140:143], off offset:320
	v_pk_mul_f32 v[30:31], v[30:31], v[156:157] op_sel_hi:[1,0]
	v_pk_mul_f32 v[32:33], v[32:33], v[156:157] op_sel_hi:[1,0]
	v_pk_mul_f32 v[26:27], v[26:27], v[156:157] op_sel_hi:[1,0]
	v_pk_mul_f32 v[28:29], v[28:29], v[156:157] op_sel_hi:[1,0]
	v_pk_mul_f32 v[22:23], v[22:23], v[156:157] op_sel_hi:[1,0]
	v_pk_mul_f32 v[24:25], v[24:25], v[156:157] op_sel_hi:[1,0]
	v_pk_mul_f32 v[18:19], v[18:19], v[156:157] op_sel_hi:[1,0]
	v_pk_mul_f32 v[20:21], v[20:21], v[156:157] op_sel_hi:[1,0]
	v_mul_f32_e32 v176, v30, v30
	v_fmac_f32_e32 v176, v31, v31
	v_fmac_f32_e32 v176, v32, v32
	v_fmac_f32_e32 v176, v33, v33
	v_fmac_f32_e32 v176, v26, v26
	v_fmac_f32_e32 v176, v27, v27
	v_fmac_f32_e32 v176, v28, v28
	v_fmac_f32_e32 v176, v29, v29
	v_fmac_f32_e32 v176, v22, v22
	v_fmac_f32_e32 v176, v23, v23
	v_fmac_f32_e32 v176, v24, v24
	v_fmac_f32_e32 v176, v25, v25
	v_fmac_f32_e32 v176, v18, v18
	v_fmac_f32_e32 v176, v19, v19
	v_fmac_f32_e32 v176, v20, v20
	v_fmac_f32_e32 v176, v21, v21
	ds_bpermute_b32 v177, v135, v176
	s_waitcnt lgkmcnt(0)
; __device__ __forceinline__ uint32_t pack2(float a, float b) { return (uint32_t)f2bf(a) | ((uint32_t)f2bf(b) << 16); }
;     ...
;           if (cls < 2) {
;             float ss = 0.f;
;             for (int m = 0; m < 4; ++m) for (int jj = 0; jj < 4; ++jj) { const float t = acc[ai][bj][m][nn][jj] * rs; ss += t * t; }
;             ss += __shfl_xor(ss, 16); ss += __shfl_xor(ss, 32);
;             hr = rsqrtf(ss * (1.f / 64.f) + EPS) * sc;
;           }
;           for (int m = 0; m < 4; ++m) {
;             const int n = nb + ai * HALF + wr * 64 + m * 16 + efq * 4;
;             float4 g4 = make_float4(1.f, 1.f, 1.f, 1.f);
;             if (cls < 2) g4 = *(const float4*)(gp + m * 16 + efq * 4);
;             const float o0 = acc[ai][bj][m][nn][0] * rs * hr * g4.x, o1 = acc[ai][bj][m][nn][1] * rs * hr * g4.y;
;             const float o2 = acc[ai][bj][m][nn][2] * rs * hr * g4.z, o3 = acc[ai][bj][m][nn][3] * rs * hr * g4.w;
;             uint2 pk; pk.x = pack2(o0, o1); pk.y = pack2(o2, o3);
;             if (cls == 0) { *(uint2*)(Qn + tok * DM + n) = pk; }
;             else {
;               float* of = pq->out + (cls == 1 ? (prompt ? O_PK + ((long)jq * TP + tok) * DM : O_SK + ((long)jq * TS + (tok - TP)) * DM)
;                                               : (prompt ? O_PV + ((long)jq * TP + tok) * DM : O_SV + ((long)jq * TS + (tok - TP)) * DM)) + n;
;               *(float4*)of = make_float4(o0, o1, o2, o3);
;               if (prompt) {
;                 if (cls == 1) *(uint2*)(Kn + tok * DM + n) = pk;
	v_add_f32_e32 v176, v176, v177
	ds_bpermute_b32 v177, v136, v176
	s_waitcnt lgkmcnt(0)
	v_add_f32_e32 v176, v176, v177
	v_fmamk_f32 v176, v176, 0x3c800000, v137
	v_rsq_f32_e32 v174, v176
	s_nop 0
	v_pk_mul_f32 v[30:31], v[30:31], v[174:175] op_sel_hi:[1,0]
	v_pk_mul_f32 v[32:33], v[32:33], v[174:175] op_sel_hi:[1,0]
	v_pk_mul_f32 v[26:27], v[26:27], v[174:175] op_sel_hi:[1,0]
	v_pk_mul_f32 v[28:29], v[28:29], v[174:175] op_sel_hi:[1,0]
	v_pk_mul_f32 v[22:23], v[22:23], v[174:175] op_sel_hi:[1,0]
	v_pk_mul_f32 v[24:25], v[24:25], v[174:175] op_sel_hi:[1,0]
	v_pk_mul_f32 v[18:19], v[18:19], v[174:175] op_sel_hi:[1,0]
	v_pk_mul_f32 v[20:21], v[20:21], v[174:175] op_sel_hi:[1,0]
	v_pk_mul_f32 v[30:31], v[30:31], v[182:183]
	v_pk_mul_f32 v[32:33], v[32:33], v[184:185]
	v_pk_mul_f32 v[26:27], v[26:27], v[186:187]
	v_pk_mul_f32 v[28:29], v[28:29], v[188:189]
	v_pk_mul_f32 v[22:23], v[22:23], v[190:191]
	v_pk_mul_f32 v[24:25], v[24:25], v[192:193]
	v_pk_mul_f32 v[18:19], v[18:19], v[194:195]
	v_pk_mul_f32 v[20:21], v[20:21], v[196:197]
	global_store_dwordx4 v[164:165], v[30:33], off
	global_store_dwordx4 v[164:165], v[26:29], off offset:64
	global_store_dwordx4 v[164:165], v[22:25], off offset:128
	global_store_dwordx4 v[164:165], v[18:21], off offset:192
	v_cvt_pk_bf16_f32 v130, v30, v31
	v_cvt_pk_bf16_f32 v131, v32, v33
	v_cvt_pk_bf16_f32 v132, v26, v27
	v_cvt_pk_bf16_f32 v133, v28, v29
	s_nop 1
	v_permlane16_swap_b32_e32 v130, v132
	v_permlane16_swap_b32_e32 v131, v133
	global_store_dwordx4 v[172:173], v[130:133], off
	v_cvt_pk_bf16_f32 v140, v22, v23
	v_cvt_pk_bf16_f32 v141, v24, v25
	v_cvt_pk_bf16_f32 v142, v18, v19
	v_cvt_pk_bf16_f32 v143, v20, v21
	s_nop 1
	v_permlane16_swap_b32_e32 v140, v142
	v_permlane16_swap_b32_e32 v141, v143
	global_store_dwordx4 v[172:173], v[140:143], off offset:64
	v_pk_mul_f32 v[14:15], v[14:15], v[156:157] op_sel_hi:[1,0]
	v_pk_mul_f32 v[16:17], v[16:17], v[156:157] op_sel_hi:[1,0]
	v_pk_mul_f32 v[10:11], v[10:11], v[156:157] op_sel_hi:[1,0]
	v_pk_mul_f32 v[12:13], v[12:13], v[156:157] op_sel_hi:[1,0]
	v_pk_mul_f32 v[6:7], v[6:7], v[156:157] op_sel_hi:[1,0]
	v_pk_mul_f32 v[8:9], v[8:9], v[156:157] op_sel_hi:[1,0]
	v_pk_mul_f32 v[2:3], v[2:3], v[156:157] op_sel_hi:[1,0]
	v_pk_mul_f32 v[4:5], v[4:5], v[156:157] op_sel_hi:[1,0]
	v_mul_f32_e32 v176, v14, v14
	v_fmac_f32_e32 v176, v15, v15
	v_fmac_f32_e32 v176, v16, v16
	v_fmac_f32_e32 v176, v17, v17
	v_fmac_f32_e32 v176, v10, v10
	v_fmac_f32_e32 v176, v11, v11
	v_fmac_f32_e32 v176, v12, v12
	v_fmac_f32_e32 v176, v13, v13
	v_fmac_f32_e32 v176, v6, v6
	v_fmac_f32_e32 v176, v7, v7
	v_fmac_f32_e32 v176, v8, v8
	v_fmac_f32_e32 v176, v9, v9
	v_fmac_f32_e32 v176, v2, v2
	v_fmac_f32_e32 v176, v3, v3
	v_fmac_f32_e32 v176, v4, v4
	v_fmac_f32_e32 v176, v5, v5
	ds_bpermute_b32 v177, v135, v176
	s_waitcnt lgkmcnt(0)
	v_add_f32_e32 v176, v176, v177
	ds_bpermute_b32 v177, v136, v176
	s_waitcnt lgkmcnt(0)
	v_add_f32_e32 v176, v176, v177
	v_fmamk_f32 v176, v176, 0x3c800000, v137
	v_rsq_f32_e32 v174, v176
	s_nop 0
	v_pk_mul_f32 v[14:15], v[14:15], v[174:175] op_sel_hi:[1,0]
	v_pk_mul_f32 v[16:17], v[16:17], v[174:175] op_sel_hi:[1,0]
	v_pk_mul_f32 v[10:11], v[10:11], v[174:175] op_sel_hi:[1,0]
	v_pk_mul_f32 v[12:13], v[12:13], v[174:175] op_sel_hi:[1,0]
	v_pk_mul_f32 v[6:7], v[6:7], v[174:175] op_sel_hi:[1,0]
	v_pk_mul_f32 v[8:9], v[8:9], v[174:175] op_sel_hi:[1,0]
	v_pk_mul_f32 v[2:3], v[2:3], v[174:175] op_sel_hi:[1,0]
	v_pk_mul_f32 v[4:5], v[4:5], v[174:175] op_sel_hi:[1,0]
	v_pk_mul_f32 v[14:15], v[14:15], v[182:183]
	v_pk_mul_f32 v[16:17], v[16:17], v[184:185]
	v_pk_mul_f32 v[10:11], v[10:11], v[186:187]
	v_pk_mul_f32 v[12:13], v[12:13], v[188:189]
	v_pk_mul_f32 v[6:7], v[6:7], v[190:191]
	v_pk_mul_f32 v[8:9], v[8:9], v[192:193]
	v_pk_mul_f32 v[2:3], v[2:3], v[194:195]
	v_pk_mul_f32 v[4:5], v[4:5], v[196:197]
	global_store_dwordx4 v[164:165], v[14:17], off offset:512
	global_store_dwordx4 v[164:165], v[10:13], off offset:576
	global_store_dwordx4 v[164:165], v[6:9], off offset:640
	global_store_dwordx4 v[164:165], v[2:5], off offset:704
	v_cvt_pk_bf16_f32 v130, v14, v15
	v_cvt_pk_bf16_f32 v131, v16, v17
	v_cvt_pk_bf16_f32 v132, v10, v11
	v_cvt_pk_bf16_f32 v133, v12, v13
	s_nop 1
	v_permlane16_swap_b32_e32 v130, v132
	v_permlane16_swap_b32_e32 v131, v133
	global_store_dwordx4 v[172:173], v[130:133], off offset:256
	v_cvt_pk_bf16_f32 v140, v6, v7
	v_cvt_pk_bf16_f32 v141, v8, v9
	v_cvt_pk_bf16_f32 v142, v2, v3
	v_cvt_pk_bf16_f32 v143, v4, v5
	s_nop 1
	v_permlane16_swap_b32_e32 v140, v142
	v_permlane16_swap_b32_e32 v141, v143
	global_store_dwordx4 v[172:173], v[140:143], off offset:320
	s_branch .Lmy_qkv_done
; __device__ __forceinline__ float rstd8(const float* q) {
;   const float4 a = *(const float4*)q, b = *(const float4*)(q + 4);
;   return rsqrtf((((a.x + a.y) + (a.z + a.w)) + ((b.x + b.y) + (b.z + b.w))) * (1.f / DM) + EPS);
; }
;     ...
;       const int cls = brow >> 10;
;       const int nb = brow & 1023;
;       const float* gp = (cls == 0 ? pq->sb_q_gain : pq->sb_k_gain) + jq * 64;
;       const float sc = (cls == 0) ? (0.125f * 1.4426950408889634f) : 1.f;
;       u16* Qn = pq->xbc; u16* Kn = pq->xbc + (long)TT * DM;
;       for (int bj = 0; bj < 2; ++bj) for (int nn = 0; nn < 2; ++nn) {
;         const long tok = bcol + bj * HALF + wc * 32 + nn * 16 + efr;
;         const float rs = rstd8(ssq_in + tok * 8);
;         const bool prompt = tok < TP;
;         for (int ai = 0; ai < 2; ++ai) {
;           float hr = 1.f;
;           if (cls < 2) {
;             float ss = 0.f;
;             for (int m = 0; m < 4; ++m) for (int jj = 0; jj < 4; ++jj) { const float t = acc[ai][bj][m][nn][jj] * rs; ss += t * t; }
;             ss += __shfl_xor(ss, 16); ss += __shfl_xor(ss, 32);
;             hr = rsqrtf(ss * (1.f / 64.f) + EPS) * sc;
.Lmy_qkv_done:
	v_readlane_b32 s4, v255, 27
	v_readlane_b32 s5, v255, 28
	s_mov_b64 s[14:15], -1
	s_nop 0
	s_and_b64 vcc, exec, s[4:5]
	s_mov_b32 s10, s92
	s_mov_b32 s4, s90
	s_cbranch_vccnz .LBB0_1089
	s_branch .LBB0_637
.Lmy_qkv_slow:
	v_mov_b32_e32 v131, v0
	s_ashr_i32 s5, s4, 10
	v_and_b32_e32 v130, 15, v131
	v_add3_u32 v138, s10, v201, v130
	v_ashrrev_i32_e32 v139, 31, v138
	v_lshlrev_b64 v[132:133], 5, v[138:139]
	v_lshl_add_u64 v[136:137], s[20:21], 0, v[132:133]
	global_load_dwordx4 v[132:135], v[136:137], off
	global_load_dwordx4 v[140:143], v[136:137], off offset:16
	s_cmpk_lt_u32 s4, 0x400
	s_cselect_b64 vcc, -1, 0
	v_mov_b32_e32 v136, 0x3e38aa3b
	v_cndmask_b32_e32 v152, 1.0, v136, vcc
	s_cmpk_gt_u32 s4, 0x3ff
	s_cselect_b64 s[18:19], -1, 0
	s_cmp_lt_i32 s5, 2
	v_mov_b32_e32 v130, 1.0
	s_cselect_b64 s[14:15], -1, 0
	s_cmp_gt_i32 s5, 1
	v_mov_b32_e32 v148, 1.0
	s_waitcnt vmcnt(1)
	v_mov_b32_e32 v136, v132
	s_waitcnt vmcnt(0)
	v_mov_b32_e32 v137, v140
	v_mov_b32_e32 v140, v133
	v_mov_b32_e32 v132, v134
	v_mov_b32_e32 v133, v142
	v_mov_b32_e32 v142, v135
	v_pk_add_f32 v[134:135], v[136:137], v[140:141]
	v_pk_add_f32 v[132:133], v[132:133], v[142:143]
	s_nop 0
	v_pk_add_f32 v[132:133], v[134:135], v[132:133]
	s_nop 0
	v_add_f32_e32 v132, v132, v133
	v_fmamk_f32 v132, v132, 0x3a800000, v225
	v_mul_f32_e32 v133, 0x4b800000, v132
	v_cmp_gt_f32_e64 s[10:11], s46, v132
	s_nop 1
	v_cndmask_b32_e64 v132, v132, v133, s[10:11]
	v_rsq_f32_e32 v132, v132
	s_nop 0
	v_mul_f32_e32 v133, 0x45800000, v132
	v_cndmask_b32_e64 v140, v132, v133, s[10:11]
	s_cbranch_scc1 .LBB0_659
	v_mul_f32_e32 v133, v127, v140
	v_mul_f32_e32 v132, v126, v140
	v_mul_f32_e32 v134, v133, v133
	v_fmac_f32_e32 v134, v132, v132
	v_mul_f32_e32 v132, v128, v140
	v_fmac_f32_e32 v134, v132, v132
	v_mul_f32_e32 v132, v129, v140
	v_fmac_f32_e32 v134, v132, v132
	v_mul_f32_e32 v132, v122, v140
	v_fmac_f32_e32 v134, v132, v132
	v_mul_f32_e32 v132, v123, v140
	v_fmac_f32_e32 v134, v132, v132
	v_mul_f32_e32 v132, v124, v140
	v_fmac_f32_e32 v134, v132, v132
	v_mul_f32_e32 v132, v125, v140
	v_fmac_f32_e32 v134, v132, v132
	v_pk_mul_f32 v[132:133], v[118:119], v[140:141] op_sel_hi:[1,0]
	s_nop 0
	v_pk_mul_f32 v[132:133], v[132:133], v[132:133]
	s_nop 0
	v_add_f32_e32 v132, v132, v134
	v_add_f32_e32 v134, v133, v132
	v_pk_mul_f32 v[132:133], v[120:121], v[140:141] op_sel_hi:[1,0]
	s_nop 0
	v_pk_mul_f32 v[132:133], v[132:133], v[132:133]
	s_nop 0
	v_add_f32_e32 v132, v132, v134
	v_add_f32_e32 v134, v133, v132
	v_pk_mul_f32 v[132:133], v[114:115], v[140:141] op_sel_hi:[1,0]
	s_nop 0
	v_pk_mul_f32 v[132:133], v[132:133], v[132:133]
	s_nop 0
	v_add_f32_e32 v132, v132, v134
	v_add_f32_e32 v134, v133, v132
	v_pk_mul_f32 v[132:133], v[116:117], v[140:141] op_sel_hi:[1,0]
	s_nop 0
	v_pk_mul_f32 v[132:133], v[132:133], v[132:133]
	s_nop 0
	v_add_f32_e32 v132, v132, v134
	v_and_b32_e32 v134, 64, v228
	v_add_f32_e32 v132, v133, v132
	v_xor_b32_e32 v133, 16, v228
	v_add_u32_e32 v134, 64, v134
	v_cmp_lt_i32_e64 s[10:11], v133, v134
	s_nop 1
	v_cndmask_b32_e64 v133, v228, v133, s[10:11]
	v_lshlrev_b32_e32 v133, 2, v133
	ds_bpermute_b32 v133, v133, v132
	s_waitcnt lgkmcnt(0)
	v_add_f32_e32 v132, v132, v133
	v_xor_b32_e32 v133, 32, v228
	v_cmp_lt_i32_e64 s[10:11], v133, v134
	s_nop 1
	v_cndmask_b32_e64 v133, v228, v133, s[10:11]
	v_lshlrev_b32_e32 v133, 2, v133
	ds_bpermute_b32 v133, v133, v132
	s_waitcnt lgkmcnt(0)
	v_add_f32_e32 v132, v132, v133
	v_fmamk_f32 v132, v132, 0x3c800000, v225
	v_mul_f32_e32 v133, 0x4b800000, v132
	v_cmp_gt_f32_e64 s[10:11], s46, v132
	s_nop 1
	v_cndmask_b32_e64 v132, v132, v133, s[10:11]
	v_rsq_f32_e32 v132, v132
	s_nop 0
	v_mul_f32_e32 v133, 0x45800000, v132
	v_cndmask_b32_e64 v132, v132, v133, s[10:11]
	v_mul_f32_e32 v148, v152, v132
